# baseline (speedup 1.0000x reference)
; DEV float4 ld_nt4(const float4* p) { const f32x4 v = __builtin_nontemporal_load((const f32x4*)p); return make_float4(v[0], v[1], v[2], v[3]); }
; DEV void phase_prenorm(const float* __restrict__ x, const float* __restrict__ w, u16* __restrict__ h) {
;   const int tid = tidx(), lane = tid & 63;
;   const int wave = blockIdx.x * NW + (tid >> 6), nwaves = gridDim.x * NW;
;   float4 tx[8];
;   if (wave < TOK) {
;     const float4* xr = (const float4*)(x + (size_t)wave * DM);
; #pragma unroll
;     for (int i = 0; i < 8; ++i) tx[i] = ld_nt4(xr + i * 64 + lane);
;   }
;     ...
;       float4 wv = ((const float4*)w)[i * 64 + lane];
.LBB0_137:
	v_readfirstlane_b32 s0, v160
	s_andn2_b32 s0, s0, 63
	s_mov_b32 s16, 0x8000
	v_or_b32_e32 v1, s0, v161
	v_readlane_b32 s0, v253, 42
	v_ashrrev_i32_e32 v2, 6, v1
	s_nop 0
	v_add_u32_e32 v98, s0, v2
	v_cmp_gt_i32_e32 vcc, s16, v98
	s_and_saveexec_b64 s[4:5], vcc
	v_writelane_b32 v253, s2, 43
	s_cbranch_execz .LBB0_142
	v_ashrrev_i32_e32 v99, 31, v98
	v_readlane_b32 s84, v253, 6
	v_and_b32_e32 v1, 63, v1
	v_lshlrev_b64 v[2:3], 13, v[98:99]
	v_readlane_b32 s85, v253, 7
	v_lshlrev_b32_e32 v66, 4, v1
	v_mov_b32_e32 v67, 0
	v_lshl_add_u64 v[2:3], s[84:85], 0, v[2:3]
	v_lshl_add_u64 v[2:3], v[2:3], 0, v[66:67]
	s_movk_i32 s0, 0x1000
	global_load_dwordx4 v[26:29], v[2:3], off nt
	global_load_dwordx4 v[30:33], v[2:3], off offset:1024 nt
	global_load_dwordx4 v[34:37], v[2:3], off offset:2048 nt
	global_load_dwordx4 v[38:41], v[2:3], off offset:3072 nt
	v_add_co_u32_e32 v2, vcc, s0, v2
	v_readlane_b32 s94, v253, 16
	s_nop 0
	v_addc_co_u32_e32 v3, vcc, 0, v3, vcc
	v_readlane_b32 s95, v253, 17
	global_load_dwordx4 v[42:45], v[2:3], off nt
	global_load_dwordx4 v[46:49], v[2:3], off offset:1024 nt
	global_load_dwordx4 v[50:53], v[2:3], off offset:2048 nt
	global_load_dwordx4 v[54:57], v[2:3], off offset:3072 nt
	global_load_dwordx4 v[2:5], v66, s[94:95]
	global_load_dwordx4 v[6:9], v66, s[94:95] offset:1024
	global_load_dwordx4 v[10:13], v66, s[94:95] offset:2048
	global_load_dwordx4 v[14:17], v66, s[94:95] offset:3072
	v_or_b32_e32 v18, 0x1000, v66
	v_or_b32_e32 v22, 0x1400, v66
	v_or_b32_e32 v58, 0x1800, v66
	v_or_b32_e32 v62, 0x1c00, v66
	global_load_dwordx4 v[18:21], v18, s[94:95]
	global_load_dwordx4 v[22:25], v22, s[94:95]
	global_load_dwordx4 v[58:61], v58, s[94:95]
	global_load_dwordx4 v[62:65], v62, s[94:95]
	s_load_dword s0, s[44:45], 0x10
	s_load_dword s6, s[44:45], 0x0
	v_lshlrev_b64 v[68:69], 12, v[98:99]
	v_lshl_or_b32 v68, v1, 3, v68
	v_lshl_add_u64 v[100:101], s[72:73], 0, v[68:69]
	s_waitcnt lgkmcnt(0)
	s_lshr_b32 s0, s0, 16
	s_cmp_lg_u32 s0, 0
	s_cselect_b64 s[0:1], -1, 0
	s_cmp_lg_u64 s[0:1], 0
	s_addc_u32 s0, s6, 0
	s_lshl_b32 s6, s0, 3
	v_add_u32_e32 v68, s6, v98
	v_ashrrev_i32_e32 v69, 31, v68
	v_lshlrev_b64 v[68:69], 13, v[68:69]
	v_or_b32_e32 v68, v68, v66
	s_ashr_i32 s7, s6, 31
	v_lshl_add_u64 v[66:67], s[84:85], 0, v[68:69]
	s_mov_b64 s[0:1], 0x1000
	s_lshl_b64 s[8:9], s[6:7], 12
	v_readlane_b32 s2, v253, 43
	v_lshl_add_u64 v[102:103], v[66:67], 0, s[0:1]
	s_lshl_b64 s[10:11], s[6:7], 13
	s_mov_b64 s[12:13], 0
	s_movk_i32 s7, 0x7fff
	v_mov_b32_e32 v1, 0x358637bd
	s_mov_b32 s17, 0x800000
	v_readlane_b32 s86, v253, 8
	v_readlane_b32 s87, v253, 9
	v_readlane_b32 s88, v253, 10
	v_readlane_b32 s89, v253, 11
	v_readlane_b32 s90, v253, 12
	v_readlane_b32 s91, v253, 13
	v_readlane_b32 s92, v253, 14
	v_readlane_b32 s93, v253, 15
	v_readlane_b32 s96, v253, 18
	v_readlane_b32 s97, v253, 19
	v_readlane_b32 s98, v253, 20
	v_readlane_b32 s99, v253, 21
	s_branch .LBB0_140

; template <int XIN, int XOUT>
; DEV void phase_resnorm(const void* xin_, const u16* __restrict__ y, const float* __restrict__ wpost,
;                        const float* __restrict__ wnext, void* xout_, u16* __restrict__ h) {
;   const int tid = tidx(), lane = tid & 63;
;   const int wave = blockIdx.x * NW + (tid >> 6), nwaves = gridDim.x * NW;
;   uint2 ty[8];
;   float4 tx[8];
;   uint2 tb[8];
;   if (wave < TOK) {
;     const uint2* yr = (const uint2*)(y + (size_t)wave * DM);
; #pragma unroll
;     for (int i = 0; i < 8; ++i) ty[i] = yr[i * 64 + lane];
;     if (XIN) {
;       const uint2* xr = (const uint2*)((const u16*)xin_ + (size_t)wave * DM);
; #pragma unroll
;       for (int i = 0; i < 8; ++i) tb[i] = xr[i * 64 + lane];
;     ...
;       float4 wv = ((const float4*)wpost)[i * 64 + lane];
.LBB0_167:
	v_readfirstlane_b32 s4, v160
	s_andn2_b32 s4, s4, 63
	s_nop 0
	v_or_b32_e32 v0, s4, v161
	v_readlane_b32 s4, v253, 42
	s_waitcnt vmcnt(0)
	v_ashrrev_i32_e32 v34, 6, v0
	v_add_u32_e32 v32, s4, v34
	v_cmp_gt_i32_e32 vcc, s60, v32
	s_and_saveexec_b64 s[10:11], vcc
	s_cbranch_execz .LBB0_174
	v_and_b32_e32 v16, 63, v0
	v_lshlrev_b32_e32 v36, 4, v16
	v_readlane_b32 s44, v253, 22
	v_ashrrev_i32_e32 v33, 31, v32
	v_readlane_b32 s45, v253, 23
	v_or_b32_e32 v50, 0x1800, v36
	v_lshlrev_b64 v[38:39], 12, v[32:33]
	v_or_b32_e32 v46, 0x1000, v36
	s_nop 1
	global_load_dwordx4 v[0:3], v36, s[44:45] offset:3072
	global_load_dwordx4 v[4:7], v36, s[44:45] offset:2048
	v_or_b32_e32 v52, 0x1c00, v36
	global_load_dwordx4 v[8:11], v50, s[44:45]
	global_load_dwordx4 v[12:15], v52, s[44:45]
	v_lshlrev_b32_e32 v128, 3, v16
	v_or_b32_e32 v48, 0x1400, v36
	global_load_dwordx4 v[16:19], v46, s[44:45]
	global_load_dwordx4 v[20:23], v48, s[44:45]
	v_lshl_add_u64 v[24:25], s[74:75], 0, v[38:39]
	v_lshl_add_u64 v[26:27], s[24:25], 0, v[38:39]
	v_lshl_add_u64 v[24:25], v[24:25], 0, v[128:129]
	v_lshl_add_u64 v[26:27], v[26:27], 0, v[128:129]
	global_load_dwordx2 v[122:123], v[26:27], off
	global_load_dwordx2 v[114:115], v[26:27], off offset:512
	global_load_dwordx2 v[124:125], v[24:25], off
	global_load_dwordx2 v[116:117], v[24:25], off offset:512
	global_load_dwordx2 v[96:97], v[24:25], off offset:3072
	global_load_dwordx2 v[94:95], v[24:25], off offset:3584
	global_load_dwordx2 v[100:101], v[26:27], off offset:3072
	global_load_dwordx2 v[98:99], v[26:27], off offset:3584
	global_load_dwordx2 v[104:105], v[24:25], off offset:2048
	global_load_dwordx2 v[102:103], v[24:25], off offset:2560
	global_load_dwordx2 v[108:109], v[26:27], off offset:2048
	global_load_dwordx2 v[106:107], v[26:27], off offset:2560
	global_load_dwordx2 v[112:113], v[24:25], off offset:1024
	global_load_dwordx2 v[110:111], v[24:25], off offset:1536
	global_load_dwordx2 v[120:121], v[26:27], off offset:1024
	global_load_dwordx2 v[118:119], v[26:27], off offset:1536
	global_load_dwordx4 v[24:27], v36, s[44:45]
	global_load_dwordx4 v[28:31], v36, s[44:45] offset:1024
	v_readlane_b32 s4, v252, 19
	v_mov_b32_e32 v37, v129
	v_mov_b32_e32 v47, v129
	v_add_u32_e32 v54, s4, v34
	v_ashrrev_i32_e32 v55, 31, v54
	v_readlane_b32 s4, v252, 13
	v_mov_b32_e32 v49, v129
	v_mov_b32_e32 v51, v129
	v_mov_b32_e32 v53, v129
	v_mov_b32_e32 v41, v129
	v_mov_b32_e32 v43, v129
	v_mov_b32_e32 v45, v129
	v_readlane_b32 s5, v252, 14
	v_or_b32_e32 v40, 0x400, v36
	v_or_b32_e32 v42, 0x800, v36
	v_or_b32_e32 v44, 0xc00, v36
	v_lshlrev_b64 v[56:57], 12, v[54:55]
	s_mov_b64 s[12:13], 0
	v_lshl_add_u64 v[34:35], s[4:5], 0, v[36:37]
	v_lshl_add_u64 v[36:37], s[72:73], 0, v[38:39]
	v_lshl_add_u64 v[38:39], s[26:27], 0, v[38:39]
	v_lshl_add_u64 v[40:41], s[4:5], 0, v[40:41]
	v_lshl_add_u64 v[42:43], s[4:5], 0, v[42:43]
	v_lshl_add_u64 v[44:45], s[4:5], 0, v[44:45]
	v_lshl_add_u64 v[46:47], s[4:5], 0, v[46:47]
	v_lshl_add_u64 v[48:49], s[4:5], 0, v[48:49]
	v_lshl_add_u64 v[50:51], s[4:5], 0, v[50:51]
	v_lshl_add_u64 v[52:53], s[4:5], 0, v[52:53]
	v_lshl_add_u64 v[54:55], s[74:75], 0, v[56:57]
	v_lshl_add_u64 v[56:57], s[24:25], 0, v[56:57]
	v_readlane_b32 s46, v253, 24
	v_readlane_b32 s47, v253, 25
	v_readlane_b32 s48, v253, 26
	v_readlane_b32 s49, v253, 27
	v_readlane_b32 s50, v253, 28
	v_readlane_b32 s51, v253, 29
	v_readlane_b32 s52, v253, 30
	v_readlane_b32 s53, v253, 31
	v_readlane_b32 s54, v253, 32
	v_readlane_b32 s55, v253, 33
	v_readlane_b32 s56, v253, 34
	v_readlane_b32 s57, v253, 35
	v_readlane_b32 s58, v253, 36
	v_readlane_b32 s59, v253, 37
	s_waitcnt vmcnt(17)
	v_mov_b64_e32 v[66:67], v[122:123]
	s_waitcnt vmcnt(16)
	v_mov_b64_e32 v[68:69], v[114:115]
	s_waitcnt vmcnt(14)
	v_mov_b64_e32 v[64:65], v[116:117]
	s_waitcnt vmcnt(13)
	v_mov_b64_e32 v[72:73], v[96:97]
	s_waitcnt vmcnt(12)
	v_mov_b64_e32 v[70:71], v[94:95]
	v_mov_b32_e32 v58, v3
	v_mov_b32_e32 v59, v7
	v_mov_b32_e32 v3, v6
	v_mov_b32_e32 v6, v0
	v_mov_b32_e32 v7, v4
	v_mov_b32_e32 v4, v1
	v_mov_b32_e32 v0, v15
	v_mov_b32_e32 v1, v11
	v_mov_b32_e32 v15, v10
	v_mov_b32_e32 v60, v12
	v_mov_b32_e32 v61, v8
	v_mov_b32_e32 v8, v13
	v_mov_b32_e32 v62, v23
	v_mov_b32_e32 v63, v19
	v_mov_b32_e32 v23, v18
	v_mov_b32_e32 v18, v20
	v_mov_b32_e32 v19, v16
	v_mov_b32_e32 v16, v21
	v_mov_b64_e32 v[20:21], v[124:125]
	s_waitcnt vmcnt(10)
	v_mov_b64_e32 v[82:83], v[98:99]
	v_mov_b64_e32 v[84:85], v[100:101]
	s_waitcnt vmcnt(8)
	v_mov_b64_e32 v[74:75], v[102:103]
	v_mov_b64_e32 v[76:77], v[104:105]
	s_waitcnt vmcnt(6)
	v_mov_b64_e32 v[86:87], v[106:107]
	v_mov_b64_e32 v[88:89], v[108:109]
	s_waitcnt vmcnt(4)
	v_mov_b64_e32 v[78:79], v[110:111]
	v_mov_b64_e32 v[80:81], v[112:113]
	s_waitcnt vmcnt(2)
	v_mov_b64_e32 v[90:91], v[118:119]
	v_mov_b64_e32 v[92:93], v[120:121]
	s_branch .LBB0_170

; template <int XIN, int XOUT>
; DEV void phase_resnorm(const void* xin_, const u16* __restrict__ y, const float* __restrict__ wpost,
;                        const float* __restrict__ wnext, void* xout_, u16* __restrict__ h) {
;   const int tid = tidx(), lane = tid & 63;
;   const int wave = blockIdx.x * NW + (tid >> 6), nwaves = gridDim.x * NW;
;   uint2 ty[8];
;   float4 tx[8];
;   uint2 tb[8];
;   if (wave < TOK) {
;     const uint2* yr = (const uint2*)(y + (size_t)wave * DM);
; #pragma unroll
;     for (int i = 0; i < 8; ++i) ty[i] = yr[i * 64 + lane];
;     if (XIN) {
;       const uint2* xr = (const uint2*)((const u16*)xin_ + (size_t)wave * DM);
; #pragma unroll
;       for (int i = 0; i < 8; ++i) tb[i] = xr[i * 64 + lane];
;     ...
;       float4 wv = ((const float4*)wpost)[i * 64 + lane];
.LBB0_175:
	v_readfirstlane_b32 s4, v160
	s_andn2_b32 s4, s4, 63
	s_nop 0
	v_or_b32_e32 v0, s4, v161
	v_readlane_b32 s4, v253, 42
	s_waitcnt vmcnt(0)
	v_ashrrev_i32_e32 v34, 6, v0
	v_add_u32_e32 v32, s4, v34
	v_cmp_gt_i32_e32 vcc, s60, v32
	s_and_saveexec_b64 s[10:11], vcc
	s_cbranch_execz .LBB0_180
	v_ashrrev_i32_e32 v33, 31, v32
	v_and_b32_e32 v4, 63, v0
	v_lshlrev_b64 v[0:1], 12, v[32:33]
	v_lshl_add_u64 v[2:3], s[74:75], 0, v[0:1]
	v_lshlrev_b32_e32 v128, 3, v4
	v_lshl_add_u64 v[0:1], s[24:25], 0, v[0:1]
	v_lshl_add_u64 v[2:3], v[2:3], 0, v[128:129]
	v_lshl_add_u64 v[0:1], v[0:1], 0, v[128:129]
	v_lshlrev_b32_e32 v38, 4, v4
	v_readlane_b32 s4, v253, 48
	global_load_dwordx2 v[102:103], v[2:3], off
	global_load_dwordx2 v[98:99], v[2:3], off offset:512
	global_load_dwordx2 v[94:95], v[2:3], off offset:1024
	global_load_dwordx2 v[90:91], v[2:3], off offset:1536
	global_load_dwordx2 v[86:87], v[2:3], off offset:2048
	global_load_dwordx2 v[82:83], v[2:3], off offset:2560
	global_load_dwordx2 v[78:79], v[2:3], off offset:3072
	global_load_dwordx2 v[74:75], v[2:3], off offset:3584
	global_load_dwordx2 v[100:101], v[0:1], off
	global_load_dwordx2 v[96:97], v[0:1], off offset:512
	global_load_dwordx2 v[92:93], v[0:1], off offset:1024
	global_load_dwordx2 v[88:89], v[0:1], off offset:1536
	global_load_dwordx2 v[84:85], v[0:1], off offset:2048
	global_load_dwordx2 v[80:81], v[0:1], off offset:2560
	global_load_dwordx2 v[76:77], v[0:1], off offset:3072
	global_load_dwordx2 v[72:73], v[0:1], off offset:3584
	v_or_b32_e32 v4, 0x400, v38
	v_readlane_b32 s5, v253, 49
	v_or_b32_e32 v8, 0x800, v38
	v_or_b32_e32 v12, 0xc00, v38
	v_or_b32_e32 v16, 0x1000, v38
	v_or_b32_e32 v20, 0x1400, v38
	v_or_b32_e32 v24, 0x1800, v38
	v_or_b32_e32 v28, 0x1c00, v38
	global_load_dwordx4 v[0:3], v38, s[4:5]
	global_load_dwordx4 v[4:7], v4, s[4:5]
	global_load_dwordx4 v[8:11], v8, s[4:5]
	global_load_dwordx4 v[12:15], v12, s[4:5]
	global_load_dwordx4 v[16:19], v16, s[4:5]
	global_load_dwordx4 v[20:23], v20, s[4:5]
	global_load_dwordx4 v[24:27], v24, s[4:5]
	global_load_dwordx4 v[28:31], v28, s[4:5]
	v_readlane_b32 s4, v252, 19
	v_lshlrev_b64 v[36:37], 13, v[32:33]
	v_or_b32_e32 v36, v36, v38
	v_add_u32_e32 v34, s4, v34
	v_ashrrev_i32_e32 v35, 31, v34
	v_readlane_b32 s4, v252, 20
	v_lshlrev_b64 v[38:39], 12, v[34:35]
	v_readlane_b32 s5, v252, 21
	s_mov_b64 s[12:13], 0
	s_waitcnt vmcnt(23)
	v_mov_b64_e32 v[40:41], v[102:103]
	v_lshl_add_u64 v[34:35], s[4:5], 0, v[36:37]
	v_lshl_add_u64 v[36:37], s[74:75], 0, v[38:39]
	v_lshl_add_u64 v[38:39], s[24:25], 0, v[38:39]
	s_waitcnt vmcnt(15)
	v_mov_b64_e32 v[42:43], v[100:101]
	s_waitcnt vmcnt(14)
	v_mov_b64_e32 v[46:47], v[96:97]
	s_waitcnt vmcnt(13)
	v_mov_b64_e32 v[50:51], v[92:93]
	s_waitcnt vmcnt(12)
	v_mov_b64_e32 v[54:55], v[88:89]
	s_waitcnt vmcnt(11)
	v_mov_b64_e32 v[58:59], v[84:85]
	s_waitcnt vmcnt(10)
	v_mov_b64_e32 v[62:63], v[80:81]
	s_waitcnt vmcnt(9)
	v_mov_b64_e32 v[66:67], v[76:77]
	s_waitcnt vmcnt(8)
	v_mov_b64_e32 v[70:71], v[72:73]
	v_mov_b64_e32 v[44:45], v[98:99]
	v_mov_b64_e32 v[48:49], v[94:95]
	v_mov_b64_e32 v[52:53], v[90:91]
	v_mov_b64_e32 v[56:57], v[86:87]
	v_mov_b64_e32 v[60:61], v[82:83]
	v_mov_b64_e32 v[64:65], v[78:79]
	v_mov_b64_e32 v[68:69], v[74:75]
	s_branch .LBB0_178

; template <int XIN, int XOUT>
; DEV void phase_resnorm(const void* xin_, const u16* __restrict__ y, const float* __restrict__ wpost,
;                        const float* __restrict__ wnext, void* xout_, u16* __restrict__ h) {
;     ...
;     if (row + nwaves < TOK) {
;       const uint2* yr = (const uint2*)(y + (size_t)(row + nwaves) * DM);
; #pragma unroll
;       for (int i = 0; i < 8; ++i) ty[i] = yr[i * 64 + lane];
;       if (XIN) {
;         const uint2* xr = (const uint2*)((const u16*)xin_ + (size_t)(row + nwaves) * DM);
; #pragma unroll
;         for (int i = 0; i < 8; ++i) tb[i] = xr[i * 64 + lane];
.LBB0_178:
	v_add_u32_e32 v32, s66, v32
	s_movk_i32 s14, 0x7fff
	v_cmp_gt_i32_e64 s[4:5], s60, v32
	v_cmp_lt_i32_e32 vcc, s14, v32
	s_and_saveexec_b64 s[14:15], s[4:5]
	s_cbranch_execz .LBB0_177
	v_lshl_add_u64 v[42:43], v[36:37], 0, v[128:129]
	v_lshl_add_u64 v[70:71], v[38:39], 0, v[128:129]
	global_load_dwordx2 v[40:41], v[42:43], off
	global_load_dwordx2 v[44:45], v[42:43], off offset:512
	global_load_dwordx2 v[48:49], v[42:43], off offset:1024
	global_load_dwordx2 v[52:53], v[42:43], off offset:1536
	global_load_dwordx2 v[56:57], v[42:43], off offset:2048
	global_load_dwordx2 v[60:61], v[42:43], off offset:2560
	global_load_dwordx2 v[64:65], v[42:43], off offset:3072
	global_load_dwordx2 v[68:69], v[42:43], off offset:3584
	global_load_dwordx2 v[42:43], v[70:71], off
	global_load_dwordx2 v[46:47], v[70:71], off offset:512
	global_load_dwordx2 v[50:51], v[70:71], off offset:1024
	global_load_dwordx2 v[54:55], v[70:71], off offset:1536
	global_load_dwordx2 v[58:59], v[70:71], off offset:2048
	global_load_dwordx2 v[62:63], v[70:71], off offset:2560
	global_load_dwordx2 v[66:67], v[70:71], off offset:3072
	global_load_dwordx2 v[70:71], v[70:71], off offset:3584
	s_branch .LBB0_177

; DEV void phase_gate(const Params& p, int l) {
;     ...
;   for (int wi = gid; wi < NCC * NTL; wi += gsz) {
;     const int cc = wi % NCC, pm = wi / NCC, col = cc * 8;
;     float h2[8], h1[8], fa0[8], fa1[8], fb0[8], fb1[8];
;     if ((pm & 31) == 0) {
; #pragma unroll
;       for (int i = 0; i < 8; ++i) { h2[i] = 0.f; h1[i] = 0.f; }
;     } else {
;       unpack8(*(const uint4*)(p.halo_a + ((size_t)(pm - 1) * 2 + 0) * DFF + col), h2);
;       unpack8(*(const uint4*)(p.halo_a + ((size_t)(pm - 1) * 2 + 1) * DFF + col), h1);
;     }
;     unpack8(*(const uint4*)(p.first_a + ((size_t)pm * 2 + 0) * DFF + col), fa0);
;     unpack8(*(const uint4*)(p.first_a + ((size_t)pm * 2 + 1) * DFF + col), fa1);
;     unpack8(*(const uint4*)(p.first_b + ((size_t)pm * 2 + 0) * DFF + col), fb0);
;     unpack8(*(const uint4*)(p.first_b + ((size_t)pm * 2 + 1) * DFF + col), fb1);
;     float g0[8], g1[8];
; #pragma unroll
;     for (int i = 0; i < 8; ++i) {
;       const float w0 = cw[col + i], w1 = cw[DFF + col + i], w2 = cw[2 * DFF + col + i], bs = cb[col + i];
;       g0[i] = gelu_tanh(bs + w0 * h2[i] + w1 * h1[i] + w2 * fa0[i]) * fb0[i];
;       g1[i] = gelu_tanh(bs + w0 * h1[i] + w1 * fa0[i] + w2 * fa1[i]) * fb1[i];
;     }
.LBB0_302:
	s_or_b64 exec, exec, s[10:11]
	v_readlane_b32 s10, v252, 38
	v_lshlrev_b64 v[24:25], 1, v[0:1]
	v_lshlrev_b64 v[0:1], 2, v[0:1]
	v_readlane_b32 s11, v252, 39
	v_mul_hi_i32_i24_e32 v3, 0x2c00, v36
	v_mul_i32_i24_e32 v2, 0x2c00, v36
	v_lshl_add_u64 v[8:9], s[10:11], 0, v[0:1]
	v_readlane_b32 s10, v252, 40
	v_readlane_b32 s11, v252, 41
	v_lshlrev_b64 v[2:3], 1, v[2:3]
	v_lshl_add_u64 v[4:5], s[20:21], 0, v[2:3]
	v_lshl_add_u64 v[6:7], s[10:11], 0, v[0:1]
	s_movk_i32 s10, 0x5000
	v_add_co_u32_e32 v0, vcc, s10, v8
	v_lshl_add_u64 v[4:5], v[4:5], 0, v[24:25]
	s_nop 0
	v_addc_co_u32_e32 v1, vcc, 0, v9, vcc
	s_movk_i32 s10, 0x2000
	global_load_dwordx4 v[38:41], v[8:9], off
	global_load_dwordx4 v[42:45], v[6:7], off
	global_load_dwordx4 v[46:49], v[0:1], off offset:2048
	global_load_dwordx4 v[50:53], v[4:5], off
	v_lshl_add_u64 v[0:1], s[22:23], 0, v[2:3]
	v_add_co_u32_e32 v2, vcc, s10, v4
	s_mov_b32 s11, 0xb000
	s_nop 0
	v_addc_co_u32_e32 v3, vcc, 0, v5, vcc
	v_add_co_u32_e32 v4, vcc, s11, v8
	v_lshl_add_u64 v[0:1], v[0:1], 0, v[24:25]
	s_nop 0
	v_addc_co_u32_e32 v5, vcc, 0, v9, vcc
	global_load_dwordx4 v[54:57], v[0:1], off
	global_load_dwordx4 v[58:61], v[4:5], off
	global_load_dwordx4 v[62:65], v[2:3], off offset:3072
	v_add_co_u32_e32 v0, vcc, s10, v0
	s_mov_b64 s[10:11], 0x5800
	s_nop 0
	v_addc_co_u32_e32 v1, vcc, 0, v1, vcc
	global_load_dwordx4 v[66:69], v[0:1], off offset:3072
	s_mov_b64 s[14:15], 0xb000
	global_load_dwordx4 v[0:3], v[8:9], off offset:16
	global_load_dwordx4 v[4:7], v[6:7], off offset:16
	v_lshl_add_u64 v[10:11], v[8:9], 0, s[10:11]
	v_lshl_add_u64 v[12:13], v[8:9], 0, s[14:15]
	global_load_dwordx4 v[8:11], v[10:11], off offset:16
	global_load_dwordx4 v[12:15], v[12:13], off offset:16
	v_add_u32_e32 v34, s64, v34
	v_add_u32_e32 v35, s12, v35
	s_waitcnt vmcnt(10)
	v_pk_fma_f32 v[30:31], v[30:31], v[38:39], v[42:43]
	v_pk_fma_f32 v[70:71], v[32:33], v[38:39], v[42:43]
	s_waitcnt vmcnt(9)
	v_pk_fma_f32 v[30:31], v[32:33], v[46:47], v[30:31]
	s_waitcnt vmcnt(8)
	v_lshlrev_b32_e32 v32, 16, v50
	v_and_b32_e32 v33, 0xffff0000, v50
	v_pk_fma_f32 v[46:47], v[46:47], v[32:33], v[70:71]
	v_lshlrev_b32_e32 v38, 16, v51
	v_and_b32_e32 v39, 0xffff0000, v51
	v_pk_fma_f32 v[26:27], v[26:27], v[40:41], v[44:45]
	v_lshlrev_b32_e32 v42, 16, v52
	v_pk_fma_f32 v[26:27], v[28:29], v[48:49], v[26:27]
	v_and_b32_e32 v43, 0xffff0000, v52
	v_lshlrev_b32_e32 v50, 16, v53
	s_waitcnt vmcnt(6)
	v_pk_fma_f32 v[30:31], v[58:59], v[32:33], v[30:31]
	s_waitcnt vmcnt(5)
	v_lshlrev_b32_e32 v32, 16, v62
	v_and_b32_e32 v33, 0xffff0000, v62
	v_pk_mul_f32 v[78:79], v[30:31], v[30:31]
	v_pk_fma_f32 v[32:33], v[58:59], v[32:33], v[46:47]
	v_fmamk_f32 v37, v78, 0xbdd2d3e8, v163
	v_fmamk_f32 v58, v79, 0xbdd2d3e8, v163
	v_mul_f32_e32 v37, v30, v37
	v_mul_f32_e32 v58, v31, v58
	v_exp_f32_e32 v37, v37
	v_exp_f32_e32 v58, v58
	v_pk_mul_f32 v[46:47], v[32:33], v[32:33]
	v_lshlrev_b32_e32 v62, 16, v63
	v_fmamk_f32 v46, v46, 0xbdd2d3e8, v163
	v_fmamk_f32 v59, v47, 0xbdd2d3e8, v163
	v_mul_f32_e32 v46, v32, v46
	v_add_f32_e32 v37, 1.0, v37
	v_add_f32_e32 v47, 1.0, v58
	v_exp_f32_e32 v78, v46
	v_rcp_f32_e32 v46, v37
	v_rcp_f32_e32 v47, v47
	v_mul_f32_e32 v58, v33, v59
	v_exp_f32_e32 v59, v58
	v_and_b32_e32 v63, 0xffff0000, v63
	v_pk_mul_f32 v[30:31], v[30:31], v[46:47]
	v_pk_fma_f32 v[46:47], v[28:29], v[40:41], v[44:45]
	v_and_b32_e32 v51, 0xffff0000, v53
	v_pk_fma_f32 v[46:47], v[48:49], v[38:39], v[46:47]
	v_lshlrev_b32_e32 v52, 16, v54
	v_and_b32_e32 v53, 0xffff0000, v54
	v_add_f32_e32 v37, 1.0, v78
	v_pk_fma_f32 v[46:47], v[60:61], v[62:63], v[46:47]
	v_pk_fma_f32 v[26:27], v[60:61], v[38:39], v[26:27]
	v_rcp_f32_e32 v58, v37
	v_pk_mul_f32 v[30:31], v[30:31], v[52:53]
	v_add_f32_e32 v37, 1.0, v59
	v_pk_mul_f32 v[52:53], v[46:47], v[46:47]
	v_pk_mul_f32 v[28:29], v[26:27], v[26:27]
	v_rcp_f32_e32 v59, v37
	v_fmamk_f32 v37, v52, 0xbdd2d3e8, v163
	v_fmamk_f32 v28, v28, 0xbdd2d3e8, v163
	v_mul_f32_e32 v37, v46, v37
	v_mul_f32_e32 v28, v26, v28
	v_fmamk_f32 v29, v29, 0xbdd2d3e8, v163
	v_exp_f32_e32 v37, v37
	v_exp_f32_e32 v38, v28
	v_mul_f32_e32 v29, v27, v29
	v_exp_f32_e32 v29, v29
	v_add_f32_e32 v28, 1.0, v37
	v_add_f32_e32 v37, 1.0, v38
	v_fmamk_f32 v38, v53, 0xbdd2d3e8, v163
	v_mul_f32_e32 v38, v47, v38
	v_add_f32_e32 v29, 1.0, v29
	v_exp_f32_e32 v40, v38
	v_rcp_f32_e32 v38, v37
	v_rcp_f32_e32 v39, v29
	v_lshlrev_b32_e32 v70, 16, v64
	v_and_b32_e32 v71, 0xffff0000, v64
	v_add_f32_e32 v29, 1.0, v40
	v_pk_mul_f32 v[26:27], v[26:27], v[38:39]
	s_waitcnt vmcnt(2)
; DEV uint32_t pack2(float a, float b) { const f32x2_t v = {a, b}; const bf16x2_t h = __builtin_convertvector(v, bf16x2_t); return __builtin_bit_cast(uint32_t, h); }
; DEV void phase_gate(const Params& p, int l) {
;     ...
;       g0[i] = gelu_tanh(bs + w0 * h2[i] + w1 * h1[i] + w2 * fa0[i]) * fb0[i];
;       g1[i] = gelu_tanh(bs + w0 * h1[i] + w1 * fa0[i] + w2 * fa1[i]) * fb1[i];
;     }
;     uint4 o0, o1;
;     o0.x = pack2(g0[0], g0[1]); o0.y = pack2(g0[2], g0[3]); o0.z = pack2(g0[4], g0[5]); o0.w = pack2(g0[6], g0[7]);
;     o1.x = pack2(g1[0], g1[1]); o1.y = pack2(g1[2], g1[3]); o1.z = pack2(g1[4], g1[5]); o1.w = pack2(g1[6], g1[7]);
;     *(uint4*)(p.g + (size_t)(pm * 256 + 0) * DFF + col) = o0;
;     *(uint4*)(p.g + (size_t)(pm * 256 + 1) * DFF + col) = o1;
	v_pk_fma_f32 v[38:39], v[22:23], v[0:1], v[4:5]
	v_pk_fma_f32 v[0:1], v[20:21], v[0:1], v[4:5]
	s_waitcnt vmcnt(1)
	v_pk_fma_f32 v[38:39], v[8:9], v[42:43], v[38:39]
	v_pk_fma_f32 v[0:1], v[22:23], v[8:9], v[0:1]
	s_waitcnt vmcnt(0)
	v_pk_fma_f32 v[38:39], v[12:13], v[70:71], v[38:39]
	v_pk_fma_f32 v[0:1], v[12:13], v[42:43], v[0:1]
	v_pk_mul_f32 v[40:41], v[38:39], v[38:39]
	v_pk_mul_f32 v[4:5], v[0:1], v[0:1]
	v_fmamk_f32 v9, v41, 0xbdd2d3e8, v163
	v_fmamk_f32 v4, v4, 0xbdd2d3e8, v163
	v_fmamk_f32 v5, v5, 0xbdd2d3e8, v163
	v_mul_f32_e32 v4, v0, v4
	v_mul_f32_e32 v5, v1, v5
	v_exp_f32_e32 v4, v4
	v_exp_f32_e32 v5, v5
	v_mul_f32_e32 v9, v39, v9
	v_exp_f32_e32 v9, v9
	v_add_f32_e32 v4, 1.0, v4
	v_add_f32_e32 v5, 1.0, v5
	v_rcp_f32_e32 v4, v4
	v_rcp_f32_e32 v5, v5
	v_lshlrev_b32_e32 v72, 16, v56
	v_and_b32_e32 v73, 0xffff0000, v56
	v_lshlrev_b32_e32 v64, 16, v65
	v_pk_mul_f32 v[0:1], v[0:1], v[4:5]
	v_and_b32_e32 v65, 0xffff0000, v65
	v_pk_mul_f32 v[4:5], v[0:1], v[72:73]
	v_add_f32_e32 v0, 1.0, v9
	v_rcp_f32_e32 v9, v0
	v_pk_fma_f32 v[0:1], v[18:19], v[2:3], v[6:7]
	v_pk_fma_f32 v[2:3], v[16:17], v[2:3], v[6:7]
	v_pk_fma_f32 v[0:1], v[10:11], v[50:51], v[0:1]
	v_pk_fma_f32 v[2:3], v[18:19], v[10:11], v[2:3]
	v_pk_fma_f32 v[0:1], v[14:15], v[64:65], v[0:1]
	v_pk_fma_f32 v[2:3], v[14:15], v[50:51], v[2:3]
	v_pk_mul_f32 v[12:13], v[0:1], v[0:1]
	v_pk_mul_f32 v[6:7], v[2:3], v[2:3]
	v_fmamk_f32 v12, v12, 0xbdd2d3e8, v163
	v_mul_f32_e32 v12, v0, v12
	v_exp_f32_e32 v12, v12
	v_fmamk_f32 v7, v7, 0xbdd2d3e8, v163
	v_fmamk_f32 v37, v40, 0xbdd2d3e8, v163
	v_fmamk_f32 v6, v6, 0xbdd2d3e8, v163
	v_mul_f32_e32 v7, v3, v7
	v_fmamk_f32 v11, v13, 0xbdd2d3e8, v163
	v_mul_f32_e32 v37, v38, v37
	v_mul_f32_e32 v6, v2, v6
	v_exp_f32_e32 v7, v7
	v_mul_f32_e32 v11, v1, v11
	v_exp_f32_e32 v37, v37
	v_exp_f32_e32 v10, v6
	v_add_f32_e32 v6, 1.0, v12
	v_exp_f32_e32 v12, v11
	v_add_f32_e32 v7, 1.0, v7
	v_add_f32_e32 v8, 1.0, v37
	v_rcp_f32_e32 v11, v7
	v_add_f32_e32 v7, 1.0, v12
	v_rcp_f32_e32 v8, v8
	v_rcp_f32_e32 v6, v6
	v_add_f32_e32 v10, 1.0, v10
	v_rcp_f32_e32 v7, v7
	v_rcp_f32_e32 v10, v10
	v_lshlrev_b32_e32 v76, 16, v68
	v_and_b32_e32 v77, 0xffff0000, v68
	v_lshlrev_b32_e32 v68, 16, v69
	v_and_b32_e32 v69, 0xffff0000, v69
	v_pk_mul_f32 v[8:9], v[38:39], v[8:9]
	v_pk_mul_f32 v[0:1], v[0:1], v[6:7]
	v_lshlrev_b32_e32 v56, 16, v57
	v_and_b32_e32 v57, 0xffff0000, v57
	v_pk_mul_f32 v[8:9], v[8:9], v[76:77]
	v_pk_mul_f32 v[2:3], v[2:3], v[10:11]
	v_pk_mul_f32 v[12:13], v[0:1], v[68:69]
	v_lshlrev_b32_e32 v54, 16, v55
	v_and_b32_e32 v55, 0xffff0000, v55
	v_pk_mul_f32 v[10:11], v[2:3], v[56:57]
	v_cvt_pk_bf16_f32 v6, v8, v9
	v_cvt_pk_bf16_f32 v7, v12, v13
	v_lshlrev_b32_e32 v12, 8, v36
	v_mov_b64_e32 v[8:9], s[80:81]
	v_rcp_f32_e32 v28, v28
	v_rcp_f32_e32 v29, v29
	v_pk_mul_f32 v[26:27], v[26:27], v[54:55]
	v_cvt_pk_bf16_f32 v3, v10, v11
	v_mad_i64_i32 v[10:11], s[10:11], v12, s85, v[8:9]
	v_cvt_pk_bf16_f32 v0, v30, v31
	v_cvt_pk_bf16_f32 v1, v26, v27
	v_cvt_pk_bf16_f32 v2, v4, v5
	v_lshl_add_u64 v[10:11], v[10:11], 0, v[24:25]
	global_store_dwordx4 v[10:11], v[0:3], off
	v_lshlrev_b32_e32 v74, 16, v66
	v_and_b32_e32 v75, 0xffff0000, v66
	v_or_b32_e32 v0, 1, v12
	v_mad_i64_i32 v[0:1], s[10:11], v0, s85, v[8:9]
	v_lshlrev_b32_e32 v66, 16, v67
	v_and_b32_e32 v67, 0xffff0000, v67
	v_pk_mul_f32 v[32:33], v[32:33], v[58:59]
	v_pk_mul_f32 v[28:29], v[46:47], v[28:29]
	s_mov_b32 s10, 0x15fff
	v_pk_mul_f32 v[32:33], v[32:33], v[74:75]
	v_pk_mul_f32 v[28:29], v[28:29], v[66:67]
	v_cmp_lt_i32_e32 vcc, s10, v34
	v_cvt_pk_bf16_f32 v4, v32, v33
	v_cvt_pk_bf16_f32 v5, v28, v29
	v_lshl_add_u64 v[0:1], v[0:1], 0, v[24:25]
	s_or_b64 s[4:5], vcc, s[4:5]
	global_store_dwordx4 v[0:1], v[4:7], off
	s_andn2_b64 exec, exec, s[4:5]
	s_cbranch_execz .LBB0_307

; DEV float bflo(uint32_t w) { return __uint_as_float(w << 16); }
; DEV float bfhi(uint32_t w) { return __uint_as_float(w & 0xffff0000u); }
; DEV float4 ld_nt4(const float4* p) { const f32x4 v = __builtin_nontemporal_load((const f32x4*)p); return make_float4(v[0], v[1], v[2], v[3]); }
; template <int XIN, int XOUT>
; DEV void phase_resnorm(const void* xin_, const u16* __restrict__ y, const float* __restrict__ wpost,
;                        const float* __restrict__ wnext, void* xout_, u16* __restrict__ h) {
;     ...
;   for (int row = wave; row < TOK; row += nwaves) {
;     float4 yv[8], xv[8];
;     float ss = 0.f;
; #pragma unroll
;     for (int i = 0; i < 8; ++i) {
;       const uint2 t = ty[i];
;       yv[i].x = bflo(t.x); yv[i].y = bfhi(t.x); yv[i].z = bflo(t.y); yv[i].w = bfhi(t.y);
;       if (XIN) { const uint2 u = tb[i]; xv[i].x = bflo(u.x); xv[i].y = bfhi(u.x); xv[i].z = bflo(u.y); xv[i].w = bfhi(u.y); }
;       else xv[i] = tx[i];
;       ss += yv[i].x * yv[i].x + yv[i].y * yv[i].y + yv[i].z * yv[i].z + yv[i].w * yv[i].w;
;     }
;     if (row + nwaves < TOK) {
;       const uint2* yr = (const uint2*)(y + (size_t)(row + nwaves) * DM);
; #pragma unroll
;       for (int i = 0; i < 8; ++i) ty[i] = yr[i * 64 + lane];
;       if (XIN) {
;         const uint2* xr = (const uint2*)((const u16*)xin_ + (size_t)(row + nwaves) * DM);
; #pragma unroll
;         for (int i = 0; i < 8; ++i) tb[i] = xr[i * 64 + lane];
;       } else {
;         const float4* xr = (const float4*)((const float*)xin_ + (size_t)(row + nwaves) * DM);
; #pragma unroll
;         for (int i = 0; i < 8; ++i) tx[i] = ld_nt4(xr + i * 64 + lane);
;       }
.LBB0_318:
	v_add_u32_e32 v82, s66, v82
	s_movk_i32 s0, 0x7fff
	v_cmp_gt_i32_e32 vcc, s60, v82
	v_cmp_lt_i32_e64 s[0:1], s0, v82
	s_waitcnt vmcnt(1)
	v_mov_b32_e32 v4, v76
	v_mov_b32_e32 v5, v77
	v_mov_b32_e32 v2, v74
	v_mov_b32_e32 v3, v75
	v_mov_b32_e32 v51, v124
	v_mov_b32_e32 v47, v125
	v_mov_b32_e32 v50, v52
	v_mov_b32_e32 v46, v53
	v_mov_b32_e32 v48, v126
	v_mov_b32_e32 v44, v127
	v_mov_b32_e32 v49, v54
	v_mov_b32_e32 v45, v55
	v_mov_b32_e32 v43, v138
	v_mov_b32_e32 v39, v139
	v_mov_b32_e32 v42, v60
	v_mov_b32_e32 v38, v61
	v_mov_b32_e32 v40, v142
	v_mov_b32_e32 v36, v143
	v_mov_b32_e32 v41, v62
	v_mov_b32_e32 v37, v63
	v_mov_b32_e32 v35, v148
	v_mov_b32_e32 v21, v149
	v_mov_b32_e32 v34, v68
	v_mov_b32_e32 v20, v69
	v_mov_b32_e32 v32, v150
	v_mov_b32_e32 v18, v151
	v_mov_b32_e32 v33, v70
	v_mov_b32_e32 v19, v71
	s_waitcnt vmcnt(0)
	v_mov_b32_e32 v12, v80
	v_mov_b32_e32 v13, v81
	v_mov_b32_e32 v10, v78
	v_mov_b32_e32 v11, v79
	s_and_saveexec_b64 s[12:13], vcc
	s_cbranch_execz .LBB0_320
	v_lshl_add_u64 v[2:3], v[98:99], 0, v[128:129]
	global_load_dwordx2 v[56:57], v[2:3], off
	global_load_dwordx2 v[58:59], v[2:3], off offset:512
	global_load_dwordx2 v[118:119], v[2:3], off offset:1024
	global_load_dwordx2 v[116:117], v[2:3], off offset:1536
	global_load_dwordx2 v[114:115], v[2:3], off offset:2048
	global_load_dwordx2 v[72:73], v[2:3], off offset:2560
	global_load_dwordx2 v[66:67], v[2:3], off offset:3072
	global_load_dwordx2 v[64:65], v[2:3], off offset:3584
	global_load_dwordx4 v[2:5], v[100:101], off offset:-4096 nt
	global_load_dwordx4 v[10:13], v[100:101], off offset:-3072 nt
	global_load_dwordx4 v[18:21], v[100:101], off offset:-2048 nt
	global_load_dwordx4 v[32:35], v[100:101], off offset:-1024 nt
	global_load_dwordx4 v[36:39], v[100:101], off nt
	global_load_dwordx4 v[40:43], v[100:101], off offset:1024 nt
	global_load_dwordx4 v[44:47], v[100:101], off offset:2048 nt
	global_load_dwordx4 v[48:51], v[100:101], off offset:3072 nt

; template <int XIN, int XOUT>
; DEV void phase_resnorm(const void* xin_, const u16* __restrict__ y, const float* __restrict__ wpost,
;                        const float* __restrict__ wnext, void* xout_, u16* __restrict__ h) {
;     ...
;   if (wave < TOK) {
;     const uint2* yr = (const uint2*)(y + (size_t)wave * DM);
; #pragma unroll
;     for (int i = 0; i < 8; ++i) ty[i] = yr[i * 64 + lane];
;     if (XIN) {
;       const uint2* xr = (const uint2*)((const u16*)xin_ + (size_t)wave * DM);
; #pragma unroll
;       for (int i = 0; i < 8; ++i) tb[i] = xr[i * 64 + lane];
;     ...
;       float4 wv = ((const float4*)wpost)[i * 64 + lane];
;     ...
;         float4 wv = ((const float4*)wnext)[i * 64 + lane];
.LBB0_325:
	s_andn2_b64 vcc, exec, s[0:1]
	s_cbranch_vccnz .LBB0_332
	v_readfirstlane_b32 s0, v160
	s_andn2_b32 s0, s0, 63
	s_nop 0
	v_or_b32_e32 v0, s0, v161
	v_readlane_b32 s0, v253, 42
	v_ashrrev_i32_e32 v66, 6, v0
	s_nop 0
	v_add_u32_e32 v64, s0, v66
	v_cmp_gt_i32_e32 vcc, s60, v64
	s_and_saveexec_b64 s[6:7], vcc
	s_cbranch_execz .LBB0_331
	v_ashrrev_i32_e32 v65, 31, v64
	v_and_b32_e32 v2, 63, v0
	v_lshlrev_b64 v[68:69], 12, v[64:65]
	v_lshl_add_u64 v[0:1], s[74:75], 0, v[68:69]
	v_lshlrev_b32_e32 v128, 3, v2
	v_lshl_add_u64 v[0:1], v[0:1], 0, v[128:129]
	global_load_dwordx2 v[140:141], v[0:1], off
	global_load_dwordx2 v[136:137], v[0:1], off offset:512
	global_load_dwordx2 v[132:133], v[0:1], off offset:1024
	global_load_dwordx2 v[124:125], v[0:1], off offset:1536
	v_lshlrev_b32_e32 v4, 4, v2
	global_load_dwordx2 v[120:121], v[0:1], off offset:2048
	global_load_dwordx2 v[116:117], v[0:1], off offset:2560
	global_load_dwordx2 v[112:113], v[0:1], off offset:3072
	global_load_dwordx2 v[108:109], v[0:1], off offset:3584
	v_lshl_add_u64 v[0:1], s[26:27], 0, v[68:69]
	v_readlane_b32 s10, v253, 61
	v_readlane_b32 s0, v253, 59
	v_lshl_add_u64 v[0:1], v[0:1], 0, v[128:129]
	v_or_b32_e32 v12, 0x400, v4
	s_waitcnt vmcnt(0)
	v_or_b32_e32 v20, 0x800, v4
	v_or_b32_e32 v28, 0xc00, v4
	v_or_b32_e32 v36, 0x1000, v4
	v_or_b32_e32 v44, 0x1400, v4
	v_or_b32_e32 v52, 0x1800, v4
	v_or_b32_e32 v60, 0x1c00, v4
	v_readlane_b32 s11, v253, 62
	v_readlane_b32 s1, v253, 60
	global_load_dwordx2 v[138:139], v[0:1], off
	global_load_dwordx2 v[134:135], v[0:1], off offset:512
	global_load_dwordx2 v[126:127], v[0:1], off offset:1024
	global_load_dwordx2 v[122:123], v[0:1], off offset:1536
	global_load_dwordx2 v[118:119], v[0:1], off offset:2048
	global_load_dwordx2 v[114:115], v[0:1], off offset:2560
	global_load_dwordx2 v[110:111], v[0:1], off offset:3072
	global_load_dwordx2 v[106:107], v[0:1], off offset:3584
	s_waitcnt vmcnt(15)
	v_mov_b64_e32 v[74:75], v[140:141]
	global_load_dwordx4 v[0:3], v4, s[10:11]
	global_load_dwordx4 v[4:7], v4, s[0:1]
	global_load_dwordx4 v[8:11], v12, s[10:11]
	global_load_dwordx4 v[12:15], v12, s[0:1]
	global_load_dwordx4 v[16:19], v20, s[10:11]
	global_load_dwordx4 v[20:23], v20, s[0:1]
	global_load_dwordx4 v[24:27], v28, s[10:11]
	global_load_dwordx4 v[28:31], v28, s[0:1]
	global_load_dwordx4 v[32:35], v36, s[10:11]
	global_load_dwordx4 v[36:39], v36, s[0:1]
	global_load_dwordx4 v[40:43], v44, s[10:11]
	global_load_dwordx4 v[44:47], v44, s[0:1]
	global_load_dwordx4 v[48:51], v52, s[10:11]
	global_load_dwordx4 v[52:55], v52, s[0:1]
	global_load_dwordx4 v[56:59], v60, s[10:11]
	global_load_dwordx4 v[60:63], v60, s[0:1]
	v_readlane_b32 s0, v252, 19
	s_mov_b64 s[10:11], 0
	s_waitcnt vmcnt(30)
	v_mov_b64_e32 v[78:79], v[136:137]
	v_add_u32_e32 v70, s0, v66
	v_ashrrev_i32_e32 v71, 31, v70
	v_lshlrev_b64 v[72:73], 12, v[70:71]
	v_lshl_add_u64 v[66:67], s[72:73], 0, v[68:69]
	v_lshl_add_u64 v[68:69], s[24:25], 0, v[68:69]
	v_lshl_add_u64 v[70:71], s[74:75], 0, v[72:73]
	v_lshl_add_u64 v[72:73], s[26:27], 0, v[72:73]
	s_waitcnt vmcnt(23)
	v_mov_b64_e32 v[76:77], v[138:139]
	s_waitcnt vmcnt(22)
	v_mov_b64_e32 v[80:81], v[134:135]
	s_waitcnt vmcnt(21)
	v_mov_b64_e32 v[84:85], v[126:127]
	s_waitcnt vmcnt(20)
	v_mov_b64_e32 v[88:89], v[122:123]
	s_waitcnt vmcnt(19)
	v_mov_b64_e32 v[92:93], v[118:119]
	s_waitcnt vmcnt(18)
	v_mov_b64_e32 v[96:97], v[114:115]
	s_waitcnt vmcnt(17)
	v_mov_b64_e32 v[100:101], v[110:111]
	s_waitcnt vmcnt(16)
	v_mov_b64_e32 v[104:105], v[106:107]
	v_mov_b64_e32 v[82:83], v[132:133]
	v_mov_b64_e32 v[86:87], v[124:125]
	v_mov_b64_e32 v[90:91], v[120:121]
	v_mov_b64_e32 v[94:95], v[116:117]
	v_mov_b64_e32 v[98:99], v[112:113]
	v_mov_b64_e32 v[102:103], v[108:109]
	s_branch .LBB0_329

; template <int XIN, int XOUT>
; DEV void phase_resnorm(const void* xin_, const u16* __restrict__ y, const float* __restrict__ wpost,
;                        const float* __restrict__ wnext, void* xout_, u16* __restrict__ h) {
;     ...
;     if (row + nwaves < TOK) {
;       const uint2* yr = (const uint2*)(y + (size_t)(row + nwaves) * DM);
; #pragma unroll
;       for (int i = 0; i < 8; ++i) ty[i] = yr[i * 64 + lane];
;       if (XIN) {
;         const uint2* xr = (const uint2*)((const u16*)xin_ + (size_t)(row + nwaves) * DM);
; #pragma unroll
;         for (int i = 0; i < 8; ++i) tb[i] = xr[i * 64 + lane];
.LBB0_329:
	v_add_u32_e32 v64, s66, v64
	s_movk_i32 s12, 0x7fff
	v_cmp_gt_i32_e64 s[0:1], s60, v64
	v_cmp_lt_i32_e32 vcc, s12, v64
	s_and_saveexec_b64 s[12:13], s[0:1]
	s_cbranch_execz .LBB0_328
	v_lshl_add_u64 v[76:77], v[70:71], 0, v[128:129]
	v_lshl_add_u64 v[104:105], v[72:73], 0, v[128:129]
	global_load_dwordx2 v[74:75], v[76:77], off
	global_load_dwordx2 v[78:79], v[76:77], off offset:512
	global_load_dwordx2 v[82:83], v[76:77], off offset:1024
	global_load_dwordx2 v[86:87], v[76:77], off offset:1536
	global_load_dwordx2 v[90:91], v[76:77], off offset:2048
	global_load_dwordx2 v[94:95], v[76:77], off offset:2560
	global_load_dwordx2 v[98:99], v[76:77], off offset:3072
	global_load_dwordx2 v[102:103], v[76:77], off offset:3584
	global_load_dwordx2 v[76:77], v[104:105], off
	global_load_dwordx2 v[80:81], v[104:105], off offset:512
	global_load_dwordx2 v[84:85], v[104:105], off offset:1024
	global_load_dwordx2 v[88:89], v[104:105], off offset:1536
	global_load_dwordx2 v[92:93], v[104:105], off offset:2048
	global_load_dwordx2 v[96:97], v[104:105], off offset:2560
	global_load_dwordx2 v[100:101], v[104:105], off offset:3072
	global_load_dwordx2 v[104:105], v[104:105], off offset:3584
	s_branch .LBB0_328

; DEV float log_gamma(int h) { return log1pf(-exp2f(-5.0f - (float)h)); }
; DEV void ret_out_item(const Params& p, int l, int item, unsigned char* smem) {
;   const int half = 1, sitem = item, h = sitem & 3, n = (sitem >> 2) & 63, b = sitem >> 8;
;   const int tid = tidx(), w = tid >> 6, lane = tid & 63, fr = lane & 15, fq = lane >> 4;
;   const int r0w = w * RW;
;   u16* sST = (u16*)(smem + L_ST);
;   u16* sP = (u16*)(smem + L_PW) + w * RW * VS;
;   const u16* base = p.proj + ((size_t)b * SEQ + n * 128) * DIN;
;   const float lg = log_gamma(h);
;   bf16x8 qf[MT][4];
;   load_qfrags(base + (size_t)r0w * DIN + C_RQ + h * 128, qf, fr, fq);
;   f32x4 o[MT][8];
; #pragma unroll
;   for (int mt = 0; mt < MT; ++mt)
; #pragma unroll
;     for (int nt = 0; nt < 8; ++nt) o[mt][nt] = (f32x4){0.f, 0.f, 0.f, 0.f};
;   uint4 kq0, kq1, vq0, vq1;
;   kv_load(base + C_RK + h * 128, base + C_RV + h * 128, kq0, kq1, vq0, vq1, tid);
;   __syncthreads();
;   {
;     const float4* st = (const float4*)(p.prev + (size_t)sitem * 16384);
;     for (int c = tid; c < 128 * 32; c += NT) {
.LBB0_341:
	v_readfirstlane_b32 s1, v160
	s_ashr_i32 s0, s4, 8
	s_andn2_b32 s1, s1, 63
	v_or_b32_e32 v38, s1, v161
	s_ashr_i32 s1, s0, 31
	s_lshl_b64 s[6:7], s[0:1], 13
	s_lshl_b32 s0, s4, 5
	s_and_b32 s0, s0, 0x1f80
	s_or_b32 s6, s6, s0
	s_and_b32 s28, s4, 3
	s_mul_i32 s0, s7, 0x2800
	v_ashrrev_i32_e32 v0, 2, v38
	s_mul_hi_u32 s1, s6, 0x2800
	v_and_b32_e32 v80, -16, v0
	s_add_i32 s1, s1, s0
	s_mul_i32 s0, s6, 0x2800
	v_cvt_f32_ubyte0_e32 v0, s28
	s_add_u32 s10, s76, s0
	v_sub_f32_e32 v39, 0xc0a00000, v0
	s_mov_b32 s0, 0xc2fc0000
	s_addc_u32 s11, s77, s1
	v_cmp_gt_f32_e32 vcc, s0, v39
	v_and_b32_e32 v90, 15, v38
	s_and_b64 s[0:1], vcc, exec
	v_mov_b64_e32 v[0:1], s[10:11]
	s_cselect_b32 s5, 0xffffffc0, 0
	v_mad_i64_i32 v[0:1], s[0:1], v80, s88, v[0:1]
	s_lshl_b32 s18, s28, 8
	v_mul_u32_u24_e32 v2, 0x1400, v90
	v_bfe_u32 v92, v38, 4, 2
	v_lshl_add_u64 v[0:1], v[0:1], 0, s[18:19]
	v_lshlrev_b32_e32 v128, 1, v2
	v_lshlrev_b32_e32 v18, 3, v38
	v_lshl_add_u64 v[0:1], v[0:1], 0, v[128:129]
	v_lshlrev_b32_e32 v128, 4, v92
	v_and_b32_e32 v18, 0x78, v18
	v_and_b32_e32 v43, 63, v38
	v_lshl_add_u64 v[0:1], v[0:1], 0, v[128:129]
	s_add_u32 s0, s10, s18
	v_lshlrev_b32_e32 v128, 1, v18
	v_mul_u32_u24_e32 v18, 0x1400, v43
	s_addc_u32 s1, s11, 0
	v_add_u32_e32 v28, 0x200, v38
	v_lshlrev_b32_e32 v32, 1, v18
	v_mov_b32_e32 v33, v129
	v_lshl_add_u64 v[22:23], s[0:1], 0, v[32:33]
	v_ashrrev_i32_e32 v18, 3, v38
	v_ashrrev_i32_e32 v33, 4, v28
	v_ashrrev_i32_e32 v28, 3, v28
	v_ashrrev_i32_e32 v42, 4, v38
	v_mov_b64_e32 v[20:21], s[0:1]
	v_and_b32_e32 v34, -8, v18
	v_and_b32_e32 v36, -8, v28
	global_load_dwordx4 v[12:15], v[0:1], off
	global_load_dwordx4 v[8:11], v[0:1], off offset:64
	global_load_dwordx4 v[4:7], v[0:1], off offset:128
	global_load_dwordx4 v[0:3], v[0:1], off offset:192
	v_mad_i64_i32 v[16:17], s[12:13], v42, s88, v[20:21]
	v_ashrrev_i32_e32 v35, 31, v34
	v_mad_i64_i32 v[20:21], s[0:1], v33, s88, v[20:21]
	v_ashrrev_i32_e32 v37, 31, v36
	v_lshl_add_u64 v[16:17], v[16:17], 0, v[128:129]
	v_lshl_add_u64 v[18:19], v[34:35], 1, v[22:23]
	v_lshl_add_u64 v[20:21], v[20:21], 0, v[128:129]
	v_lshl_add_u64 v[22:23], v[36:37], 1, v[22:23]
	global_load_dwordx4 v[24:27], v[16:17], off offset:1024
	global_load_dwordx4 v[16:19], v[18:19], off offset:2048
	global_load_dwordx4 v[28:31], v[20:21], off offset:1024
	global_load_dwordx4 v[20:23], v[22:23], off offset:2048
	v_cndmask_b32_e32 v40, 0, v167, vcc
	v_add_f32_e32 v39, v39, v40
	v_exp_f32_e32 v39, v39
	s_mov_b32 s0, 0x3f2aaaab
	s_barrier
	v_ldexp_f32 v64, v39, s5
	v_sub_f32_e32 v44, 1.0, v64
	v_frexp_mant_f32_e32 v39, v44
	v_cmp_gt_f32_e32 vcc, s0, v39
	v_cmp_gt_i32_e64 s[0:1], s61, v38
	s_and_saveexec_b64 s[12:13], s[0:1]
	s_mov_b32 s18, 0x16100
	s_cbranch_execz .LBB0_344
	s_ashr_i32 s5, s4, 31
	s_lshl_b64 s[0:1], s[4:5], 16
	v_readlane_b32 s5, v252, 30
	s_add_u32 s0, s5, s0
	v_readlane_b32 s5, v252, 31
	v_ashrrev_i32_e32 v39, 31, v38
	s_addc_u32 s1, s5, s1
	v_lshl_add_u64 v[40:41], v[38:39], 4, s[0:1]
	v_lshlrev_b32_e32 v39, 2, v38
	s_mov_b64 s[14:15], 0

; DEV f32x4 mfma16(bf16x8 a, bf16x8 b, f32x4 c) { return __builtin_amdgcn_mfma_f32_16x16x32_bf16(a, b, c, 0, 0, 0); }
; DEV float log_gamma(int h) { return log1pf(-exp2f(-5.0f - (float)h)); }
; DEV void ret_out_item(const Params& p, int l, int item, unsigned char* smem) {
;     ...
;   kv_store(kq0, kq1, vq0, vq1, (u16*)(smem + L_K), (u16*)(smem + L_VT), tid);
;   kv_load(base + (size_t)64 * DIN + C_RK + h * 128, base + (size_t)64 * DIN + C_RV + h * 128, kq0, kq1, vq0, vq1, tid);
;   __syncthreads();
; #pragma unroll
;   for (int ks = 0; ks < 4; ++ks)
; #pragma unroll
;     for (int nt = 0; nt < 8; ++nt) {
;       bf16x8 bb = *(const bf16x8*)(sST + (nt * 16 + fr) * KS + ks * 32 + fq * 8);
; #pragma unroll
;       for (int mt = 0; mt < MT; ++mt) o[mt][nt] = mfma16(qf[mt][ks], bb, o[mt][nt]);
;     }
.LBB0_344:
	s_mov_b32 s14, 0x16100
	s_or_b64 exec, exec, s[12:13]
	v_add_f32_e32 v38, -1.0, v44
	v_sub_f32_e32 v39, v38, v44
	v_add_f32_e32 v39, 1.0, v39
	v_sub_f32_e64 v38, -v64, v38
	v_add_f32_e32 v40, v38, v39
	v_cvt_f64_f32_e32 v[38:39], v44
	v_frexp_exp_i32_f64_e32 v38, v[38:39]
	v_subbrev_co_u32_e32 v38, vcc, 0, v38, vcc
	v_sub_u32_e32 v39, 0, v38
	v_ldexp_f32 v41, v44, v39
	v_ldexp_f32 v39, v40, v39
	v_add_f32_e32 v40, -1.0, v41
	v_add_f32_e32 v46, 1.0, v41
	v_add_f32_e32 v44, 1.0, v40
	v_add_f32_e32 v47, -1.0, v46
	v_sub_f32_e32 v44, v41, v44
	v_sub_f32_e32 v41, v41, v47
	v_add_f32_e32 v44, v39, v44
	v_add_f32_e32 v39, v39, v41
	v_add_f32_e32 v41, v46, v39
	v_rcp_f32_e32 v47, v41
	v_add_f32_e32 v45, v40, v44
	v_sub_f32_e32 v40, v45, v40
	v_sub_f32_e32 v40, v44, v40
	v_sub_f32_e32 v44, v41, v46
	v_sub_f32_e32 v39, v39, v44
	v_mul_f32_e32 v44, v45, v47
	v_mul_f32_e32 v46, v41, v44
	v_fma_f32 v48, v44, v41, -v46
	v_fmac_f32_e32 v48, v44, v39
	v_add_f32_e32 v49, v46, v48
	v_sub_f32_e32 v50, v45, v49
	v_sub_f32_e32 v45, v45, v50
	v_sub_f32_e32 v46, v49, v46
	v_sub_f32_e32 v45, v45, v49
	v_add_f32_e32 v40, v40, v45
	v_sub_f32_e32 v45, v46, v48
	v_add_f32_e32 v40, v45, v40
	v_add_f32_e32 v45, v50, v40
	v_mul_f32_e32 v46, v47, v45
	v_mul_f32_e32 v48, v41, v46
	v_fma_f32 v41, v46, v41, -v48
	v_fmac_f32_e32 v41, v46, v39
	v_sub_f32_e32 v39, v50, v45
	v_add_f32_e32 v39, v40, v39
	v_add_f32_e32 v40, v48, v41
	v_sub_f32_e32 v49, v45, v40
	v_sub_f32_e32 v45, v45, v49
	v_sub_f32_e32 v48, v40, v48
	v_sub_f32_e32 v40, v45, v40
	v_add_f32_e32 v39, v39, v40
	v_sub_f32_e32 v40, v48, v41
	v_cvt_f32_i32_e32 v38, v38
	v_add_f32_e32 v39, v40, v39
	v_add_f32_e32 v40, v44, v46
	v_add_f32_e32 v39, v49, v39
	v_sub_f32_e32 v41, v40, v44
	v_mul_f32_e32 v39, v47, v39
	v_sub_f32_e32 v41, v46, v41
	v_add_f32_e32 v39, v41, v39
	v_mul_f32_e32 v54, 0x3f317218, v38
	s_mov_b32 s0, 0x3f317218
	v_add_f32_e32 v52, v40, v39
	v_fma_f32 v55, v38, s0, -v54
	v_mul_f32_e32 v53, v52, v52
	v_fmac_f32_e32 v55, 0xb102e308, v38
	v_sub_f32_e32 v38, v52, v40
	v_mad_u64_u32 v[86:87], s[0:1], v42, s89, v[128:129]
	v_fmamk_f32 v41, v53, 0x3e9b6dac, v164
	v_sub_f32_e32 v38, v39, v38
	s_lshl_b32 s5, s28, 7
	s_waitcnt vmcnt(3)
	ds_write_b128 v86, v[24:27]
	v_lshlrev_b32_e32 v24, 1, v43
	v_fmaak_f32 v56, v53, v41, 0x3f2aaada
	v_ldexp_f32 v66, v38, 1
	v_mad_i64_i32 v[40:41], s[0:1], v42, s88, 0
	v_mad_i64_i32 v[38:39], s[0:1], v33, s88, 0
	v_mad_u64_u32 v[88:89], s[0:1], v33, s89, v[128:129]
	v_mad_u64_u32 v[82:83], s[0:1], v34, s30, v[24:25]
	v_mad_u64_u32 v[84:85], s[0:1], v36, s30, v[24:25]
	s_lshl_b32 s18, s5, 1
	s_add_u32 s0, s10, s18
	s_addc_u32 s1, s11, 0
	s_add_u32 s10, s0, 0xa0400
	v_mov_b32_e32 v33, v129
	s_waitcnt vmcnt(1)
	ds_write_b128 v88, v[28:31]
	ds_write_b16 v82, v16 offset:34816
	ds_write_b16_d16_hi v82, v16 offset:34960
	ds_write_b16 v82, v17 offset:35104
	ds_write_b16_d16_hi v82, v17 offset:35248
	ds_write_b16 v82, v18 offset:35392
	ds_write_b16_d16_hi v82, v18 offset:35536
	ds_write_b16 v82, v19 offset:35680
	ds_write_b16_d16_hi v82, v19 offset:35824
	s_addc_u32 s11, s1, 0
	v_lshl_add_u64 v[18:19], s[0:1], 0, v[32:33]
	s_mov_b64 s[0:1], 0xa0800
	v_lshl_add_u64 v[16:17], s[10:11], 0, v[40:41]
	v_lshl_add_u64 v[18:19], v[18:19], 0, s[0:1]
	v_lshlrev_b32_e32 v44, 3, v92
	s_waitcnt vmcnt(0)
	ds_write_b16 v84, v20 offset:34816
	ds_write_b16_d16_hi v84, v20 offset:34960
	ds_write_b16 v84, v21 offset:35104
	ds_write_b16_d16_hi v84, v21 offset:35248
	ds_write_b16 v84, v22 offset:35392
	ds_write_b16_d16_hi v84, v22 offset:35536
	ds_write_b16 v84, v23 offset:35680
	ds_write_b16_d16_hi v84, v23 offset:35824
	v_lshl_add_u64 v[16:17], v[16:17], 0, v[128:129]
	v_lshl_add_u64 v[20:21], v[34:35], 1, v[18:19]
	global_load_dwordx4 v[24:27], v[16:17], off
	global_load_dwordx4 v[20:23], v[20:21], off
	v_lshl_add_u64 v[16:17], s[10:11], 0, v[38:39]
	v_lshlrev_b32_e32 v91, 1, v44
	v_mul_u32_u24_e32 v32, 0x110, v90
	v_lshl_add_u64 v[16:17], v[16:17], 0, v[128:129]
	v_lshl_add_u64 v[18:19], v[36:37], 1, v[18:19]
	v_add3_u32 v57, v32, v91, s14
	global_load_dwordx4 v[28:31], v[16:17], off
	global_load_dwordx4 v[16:19], v[18:19], off
	s_waitcnt lgkmcnt(0)
	s_barrier
	ds_read_b128 v[32:35], v57
	ds_read_b128 v[76:79], v57 offset:64
	s_waitcnt lgkmcnt(1)
	v_mfma_f32_16x16x32_bf16 v[32:35], v[12:15], v[32:35], 0
	ds_read_b128 v[36:39], v57 offset:4352
	ds_read_b128 v[40:43], v57 offset:8704
	ds_read_b128 v[44:47], v57 offset:13056
	s_waitcnt lgkmcnt(3)
	v_mfma_f32_16x16x32_bf16 v[32:35], v[8:11], v[76:79], v[32:35]
	ds_read_b128 v[76:79], v57 offset:4416
	ds_read_b128 v[48:51], v57 offset:17408
	ds_read_b128 v[58:61], v57 offset:21760
	s_waitcnt lgkmcnt(5)
	v_mfma_f32_16x16x32_bf16 v[36:39], v[12:15], v[36:39], 0
	ds_read_b128 v[68:71], v57 offset:26112
	ds_read_b128 v[72:75], v57 offset:30464
	v_add_f32_e32 v83, v54, v55
	s_waitcnt lgkmcnt(4)
	v_mfma_f32_16x16x32_bf16 v[36:39], v[8:11], v[76:79], v[36:39]
	ds_read_b128 v[76:79], v57 offset:8768
	v_sub_f32_e32 v54, v83, v54
	v_ldexp_f32 v67, v52, 1
	v_mfma_f32_16x16x32_bf16 v[40:43], v[12:15], v[40:43], 0
	v_sub_f32_e32 v85, v55, v54
	v_cmp_nlt_f32_e32 vcc, 1.0, v64
	s_mov_b32 s0, 0x33800000
	s_waitcnt lgkmcnt(0)
	v_mfma_f32_16x16x32_bf16 v[40:43], v[8:11], v[76:79], v[40:43]
	ds_read_b128 v[76:79], v57 offset:13120
	v_xor_b32_e32 v65, 0x80000000, v64
	v_ashrrev_i32_e32 v81, 31, v80
	v_mfma_f32_16x16x32_bf16 v[44:47], v[12:15], v[44:47], 0
	s_waitcnt lgkmcnt(0)
	v_mfma_f32_16x16x32_bf16 v[44:47], v[8:11], v[76:79], v[44:47]
	ds_read_b128 v[76:79], v57 offset:17472
	v_mfma_f32_16x16x32_bf16 v[48:51], v[12:15], v[48:51], 0
	s_waitcnt lgkmcnt(0)
; DEV f32x4 mfma16(bf16x8 a, bf16x8 b, f32x4 c) { return __builtin_amdgcn_mfma_f32_16x16x32_bf16(a, b, c, 0, 0, 0); }
; DEV void ret_out_item(const Params& p, int l, int item, unsigned char* smem) {
;     ...
; #pragma unroll
;   for (int ks = 0; ks < 4; ++ks)
; #pragma unroll
;     for (int nt = 0; nt < 8; ++nt) {
;       bf16x8 bb = *(const bf16x8*)(sST + (nt * 16 + fr) * KS + ks * 32 + fq * 8);
; #pragma unroll
;       for (int mt = 0; mt < MT; ++mt) o[mt][nt] = mfma16(qf[mt][ks], bb, o[mt][nt]);
;     }
; #pragma unroll
;   for (int mt = 0; mt < MT; ++mt)
; #pragma unroll
;     for (int j = 0; j < 4; ++j) {
;       const float xi = __expf(lg * (float)(r0w + mt * 16 + fq * 4 + j + 1));
; #pragma unroll
;       for (int nt = 0; nt < 8; ++nt) o[mt][nt][j] *= xi;
;     }
;   for (int jh = 0; jh <= half; ++jh) {
;     u16* sK = (u16*)(smem + L_K + jh * KB_B); u16* sVt = (u16*)(smem + L_VT + jh * VB_B);
;     if (jh == 1) { kv_store(kq0, kq1, vq0, vq1, sK, sVt, tid); __syncthreads(); }
;     f32x4 s[MT][4];
;     qk_tile(qf, sK, s, fr, fq);
; #pragma unroll
;     for (int mt = 0; mt < MT; ++mt)
; #pragma unroll
;       for (int j = 0; j < 4; ++j) {
;         const int i = r0w + mt * 16 + fq * 4 + j;
; #pragma unroll
;         for (int jt = 0; jt < 4; ++jt) {
;           const int jj = jh * 64 + jt * 16 + fr;
;           const float pr = (i >= jj) ? s[mt][jt][j] * 0.08838834764831845f * __expf(lg * (float)(i - jj)) : 0.f;
;           sP[(mt * 16 + fq * 4 + j) * VS + jt * 16 + fr] = f2bf(pr);
;         }
;       }
	v_mfma_f32_16x16x32_bf16 v[48:51], v[8:11], v[76:79], v[48:51]
	ds_read_b128 v[76:79], v57 offset:21824
	v_mfma_f32_16x16x32_bf16 v[58:61], v[12:15], v[58:61], 0
	s_waitcnt lgkmcnt(0)
	v_mfma_f32_16x16x32_bf16 v[58:61], v[8:11], v[76:79], v[58:61]
	ds_read_b128 v[76:79], v57 offset:26176
	v_mfma_f32_16x16x32_bf16 v[68:71], v[12:15], v[68:71], 0
	s_waitcnt lgkmcnt(0)
	v_mfma_f32_16x16x32_bf16 v[68:71], v[8:11], v[76:79], v[68:71]
	ds_read_b128 v[76:79], v57 offset:30528
	v_mfma_f32_16x16x32_bf16 v[72:75], v[12:15], v[72:75], 0
	s_waitcnt lgkmcnt(0)
	v_mfma_f32_16x16x32_bf16 v[72:75], v[8:11], v[76:79], v[72:75]
	ds_read_b128 v[76:79], v57 offset:128
	s_waitcnt lgkmcnt(0)
	v_mfma_f32_16x16x32_bf16 v[32:35], v[4:7], v[76:79], v[32:35]
	ds_read_b128 v[76:79], v57 offset:4480
	s_waitcnt lgkmcnt(0)
	v_mfma_f32_16x16x32_bf16 v[36:39], v[4:7], v[76:79], v[36:39]
	ds_read_b128 v[76:79], v57 offset:8832
	s_waitcnt lgkmcnt(0)
	v_mfma_f32_16x16x32_bf16 v[40:43], v[4:7], v[76:79], v[40:43]
	ds_read_b128 v[76:79], v57 offset:13184
	s_waitcnt lgkmcnt(0)
	v_mfma_f32_16x16x32_bf16 v[44:47], v[4:7], v[76:79], v[44:47]
	ds_read_b128 v[76:79], v57 offset:17536
	s_waitcnt lgkmcnt(0)
	v_mfma_f32_16x16x32_bf16 v[48:51], v[4:7], v[76:79], v[48:51]
	ds_read_b128 v[76:79], v57 offset:21888
	s_waitcnt lgkmcnt(0)
	v_mfma_f32_16x16x32_bf16 v[58:61], v[4:7], v[76:79], v[58:61]
	ds_read_b128 v[76:79], v57 offset:26240
	s_waitcnt lgkmcnt(0)
	v_mfma_f32_16x16x32_bf16 v[68:71], v[4:7], v[76:79], v[68:71]
	ds_read_b128 v[76:79], v57 offset:30592
	s_waitcnt lgkmcnt(0)
	v_mfma_f32_16x16x32_bf16 v[72:75], v[4:7], v[76:79], v[72:75]
	ds_read_b128 v[76:79], v57 offset:192
	s_waitcnt lgkmcnt(0)
	v_mfma_f32_16x16x32_bf16 v[32:35], v[0:3], v[76:79], v[32:35]
	ds_read_b128 v[76:79], v57 offset:4544
	s_waitcnt lgkmcnt(0)
	v_mfma_f32_16x16x32_bf16 v[36:39], v[0:3], v[76:79], v[36:39]
	ds_read_b128 v[76:79], v57 offset:8896
	s_waitcnt lgkmcnt(0)
	v_mfma_f32_16x16x32_bf16 v[40:43], v[0:3], v[76:79], v[40:43]
	ds_read_b128 v[76:79], v57 offset:13248
	ds_read_b128 v[94:97], v57 offset:17600
	ds_read_b128 v[98:101], v57 offset:21952
	s_waitcnt lgkmcnt(2)
	v_mfma_f32_16x16x32_bf16 v[44:47], v[0:3], v[76:79], v[44:47]
	ds_read_b128 v[76:79], v57 offset:26304
	ds_read_b128 v[102:105], v57 offset:30656
	v_mul_f32_e32 v57, v52, v53
	v_mul_f32_e32 v89, v57, v56
	v_mul_u32_u24_e32 v56, 0x88, v90
	v_lshl_add_u32 v87, v56, 1, v91
	s_waitcnt lgkmcnt(2)
	v_mfma_f32_16x16x32_bf16 v[52:55], v[0:3], v[98:101], v[58:61]
	v_add_f32_e32 v93, v67, v89
	v_sub_f32_e32 v67, v93, v67
	v_sub_f32_e32 v67, v89, v67
	s_waitcnt lgkmcnt(1)
	v_mfma_f32_16x16x32_bf16 v[56:59], v[0:3], v[76:79], v[68:71]
	s_nop 2
	ds_read_b128 v[68:71], v87 offset:64
	ds_read_b128 v[76:79], v87
	v_add_f32_e32 v66, v66, v67
	v_add_f32_e32 v89, v93, v66
	v_mfma_f32_16x16x32_bf16 v[48:51], v[0:3], v[94:97], v[48:51]
	v_add_f32_e32 v122, v83, v89
	v_sub_f32_e32 v114, v122, v83
	v_sub_f32_e32 v67, v89, v93
	s_waitcnt lgkmcnt(2)
	v_mfma_f32_16x16x32_bf16 v[60:63], v[0:3], v[102:105], v[72:75]
	s_nop 2
	ds_read_b128 v[72:75], v87 offset:4416
	ds_read_b128 v[94:97], v87 offset:4352
	ds_read_b128 v[98:101], v87 offset:8768
	ds_read_b128 v[102:105], v87 offset:8704
	ds_read_b128 v[106:109], v87 offset:13120
	ds_read_b128 v[110:113], v87 offset:13056
	s_waitcnt lgkmcnt(6)
	v_mfma_f32_16x16x32_bf16 v[76:79], v[12:15], v[76:79], 0
	v_sub_f32_e32 v115, v122, v114
	v_sub_f32_e32 v93, v66, v67
	s_waitcnt lgkmcnt(4)
	v_mfma_f32_16x16x32_bf16 v[94:97], v[12:15], v[94:97], 0
	s_waitcnt lgkmcnt(2)
	v_mfma_f32_16x16x32_bf16 v[102:105], v[12:15], v[102:105], 0
	s_waitcnt lgkmcnt(0)
	v_mfma_f32_16x16x32_bf16 v[110:113], v[12:15], v[110:113], 0
	v_mfma_f32_16x16x32_bf16 v[66:69], v[8:11], v[68:71], v[76:79]
	v_sub_f32_e32 v70, v83, v115
	v_sub_f32_e32 v71, v89, v114
	s_nop 0
	v_add_f32_e32 v78, v71, v70
	v_mfma_f32_16x16x32_bf16 v[70:73], v[8:11], v[72:75], v[94:97]
	v_add_f32_e32 v79, v85, v93
	v_sub_f32_e32 v83, v79, v85
	v_add_f32_e32 v78, v79, v78
	v_mfma_f32_16x16x32_bf16 v[74:77], v[8:11], v[98:101], v[102:105]
	ds_read_b128 v[94:97], v87 offset:192
	ds_read_b128 v[98:101], v87 offset:128
	v_sub_f32_e32 v89, v79, v83
	v_sub_f32_e32 v85, v85, v89
	v_mfma_f32_16x16x32_bf16 v[102:105], v[8:11], v[106:109], v[110:113]
	ds_read_b128 v[106:109], v87 offset:4544
	s_nop 1
	ds_read_b128 v[110:113], v87 offset:4480
	v_sub_f32_e32 v83, v93, v83
	v_add_f32_e32 v83, v83, v85
	s_waitcnt lgkmcnt(2)
	v_mfma_f32_16x16x32_bf16 v[66:69], v[4:7], v[98:101], v[66:69]
	ds_read_b128 v[98:101], v87 offset:8896
	ds_read_b128 v[114:117], v87 offset:8832
	s_waitcnt lgkmcnt(2)
	v_mfma_f32_16x16x32_bf16 v[70:73], v[4:7], v[110:113], v[70:73]
	ds_read_b128 v[110:113], v87 offset:13248
	ds_read_b128 v[118:121], v87 offset:13184
	s_waitcnt lgkmcnt(2)
	v_mfma_f32_16x16x32_bf16 v[114:117], v[4:7], v[114:117], v[74:77]
	s_nop 2
	v_add_f32_e32 v74, v122, v78
	v_sub_f32_e32 v75, v74, v122
	v_sub_f32_e32 v75, v78, v75
	s_waitcnt lgkmcnt(0)
	v_mfma_f32_16x16x32_bf16 v[102:105], v[4:7], v[118:121], v[102:105]
	v_add_f32_e32 v75, v83, v75
	v_add_f32_e32 v74, v74, v75
	v_lshlrev_b32_e32 v83, 2, v92
	v_mfma_f32_16x16x32_bf16 v[76:79], v[0:3], v[94:97], v[66:69]
	v_or_b32_e32 v89, v83, v80
	v_mov_b32_e32 v94, 0
	v_mov_b32_e32 v96, 0
	v_cndmask_b32_e32 v66, v168, v74, vcc
	v_cmp_neq_f32_e32 vcc, 1.0, v64
	v_mfma_f32_16x16x32_bf16 v[72:75], v[0:3], v[106:109], v[70:73]
	s_nop 0
	v_cndmask_b32_e32 v66, v169, v66, vcc
	v_cmp_gt_f32_e32 vcc, s0, v64
	v_mfma_f32_16x16x32_bf16 v[68:71], v[0:3], v[98:101], v[114:117]
	s_nop 0
	v_cndmask_b32_e32 v85, v66, v65, vcc
	v_cmp_ge_i32_e32 vcc, v89, v90
	v_mfma_f32_16x16x32_bf16 v[64:67], v[0:3], v[110:113], v[102:105]
	s_and_saveexec_b64 s[0:1], vcc
	s_cbranch_execz .LBB0_346
	v_sub_u32_e32 v93, v89, v90
	v_cvt_f32_i32_e32 v93, v93
	v_mul_f32_e32 v76, 0x3db504f3, v76
	v_mul_f32_e32 v93, v85, v93
	v_mul_f32_e32 v93, 0x3fb8aa3b, v93
	v_exp_f32_e32 v93, v93
	s_nop 0
	v_mul_f32_e32 v76, v93, v76
	v_cvt_pk_bf16_f32 v96, v76, s0

; DEV float log_gamma(int h) { return log1pf(-exp2f(-5.0f - (float)h)); }
; DEV void phase_ret_scan(const Params& p) {
;     ...
;   for (int wi = gid; wi < 16 * 8192; wi += gsz) {
;     const int idx2 = wi & 8191, bh = wi >> 13, h = bh & 3, b = bh >> 2;
;     const float decay = __expf(log_gamma(h) * 128.0f);
;     float2 run = make_float2(0.f, 0.f);
; #pragma unroll 1
;     for (int n0 = 0; n0 < 64; n0 += 16) {
;       float2 c[16];
; #pragma unroll
;       for (int k = 0; k < 16; ++k) c[k] = src[((size_t)((b * 64 + n0 + k) * 4 + h)) * 8192 + idx2];
; #pragma unroll
;       for (int k = 0; k < 16; ++k) {
;         dst[((size_t)((b * 64 + n0 + k) * 4 + h)) * 8192 + idx2] = run;
;         run.x = run.x * decay + c[k].x; run.y = run.y * decay + c[k].y;
;       }
;     }
;   }
.LBB0_413:
	v_subrev_u32_e32 v12, 60, v8
	v_subrev_u32_e32 v14, 56, v8
	s_waitcnt vmcnt(0)
	v_subrev_u32_e32 v16, 52, v8
	v_subrev_u32_e32 v18, 48, v8
	v_subrev_u32_e32 v20, 44, v8
	v_subrev_u32_e32 v22, 40, v8
	v_subrev_u32_e32 v24, 36, v8
	v_subrev_u32_e32 v26, 32, v8
	v_subrev_u32_e32 v28, 28, v8
	v_subrev_u32_e32 v30, 24, v8
	v_subrev_u32_e32 v32, 20, v8
	v_add_u32_e32 v34, -16, v8
	v_add_u32_e32 v36, -12, v8
	v_add_u32_e32 v38, -8, v8
	v_add_u32_e32 v40, -4, v8
	v_ashrrev_i32_e32 v9, 31, v8
	v_ashrrev_i32_e32 v13, 31, v12
	v_ashrrev_i32_e32 v15, 31, v14
	v_ashrrev_i32_e32 v17, 31, v16
	v_ashrrev_i32_e32 v19, 31, v18
	v_ashrrev_i32_e32 v21, 31, v20
	v_ashrrev_i32_e32 v23, 31, v22
	v_ashrrev_i32_e32 v25, 31, v24
	v_ashrrev_i32_e32 v27, 31, v26
	v_ashrrev_i32_e32 v29, 31, v28
	v_ashrrev_i32_e32 v31, 31, v30
	v_ashrrev_i32_e32 v33, 31, v32
	v_ashrrev_i32_e32 v35, 31, v34
	v_ashrrev_i32_e32 v37, 31, v36
	v_ashrrev_i32_e32 v39, 31, v38
	v_ashrrev_i32_e32 v41, 31, v40
	v_lshlrev_b64 v[42:43], 16, v[8:9]
	v_lshlrev_b64 v[12:13], 16, v[12:13]
	v_lshlrev_b64 v[14:15], 16, v[14:15]
	v_lshlrev_b64 v[16:17], 16, v[16:17]
	v_lshlrev_b64 v[18:19], 16, v[18:19]
	v_lshlrev_b64 v[20:21], 16, v[20:21]
	v_lshlrev_b64 v[22:23], 16, v[22:23]
	v_lshlrev_b64 v[24:25], 16, v[24:25]
	v_lshlrev_b64 v[26:27], 16, v[26:27]
	v_lshlrev_b64 v[28:29], 16, v[28:29]
	v_lshlrev_b64 v[30:31], 16, v[30:31]
	v_lshlrev_b64 v[32:33], 16, v[32:33]
	v_lshlrev_b64 v[34:35], 16, v[34:35]
	v_lshlrev_b64 v[36:37], 16, v[36:37]
	v_lshlrev_b64 v[38:39], 16, v[38:39]
	v_lshlrev_b64 v[40:41], 16, v[40:41]
	v_lshl_add_u64 v[44:45], v[4:5], 0, v[42:43]
	v_lshl_add_u64 v[46:47], v[4:5], 0, v[12:13]
	v_lshl_add_u64 v[48:49], v[4:5], 0, v[14:15]
	v_lshl_add_u64 v[50:51], v[4:5], 0, v[16:17]
	v_lshl_add_u64 v[52:53], v[4:5], 0, v[18:19]
	v_lshl_add_u64 v[54:55], v[4:5], 0, v[20:21]
	v_lshl_add_u64 v[56:57], v[4:5], 0, v[22:23]
	v_lshl_add_u64 v[58:59], v[4:5], 0, v[24:25]
	v_lshl_add_u64 v[60:61], v[4:5], 0, v[26:27]
	v_lshl_add_u64 v[62:63], v[4:5], 0, v[28:29]
	v_lshl_add_u64 v[64:65], v[4:5], 0, v[30:31]
	v_lshl_add_u64 v[66:67], v[4:5], 0, v[32:33]
	v_lshl_add_u64 v[68:69], v[4:5], 0, v[34:35]
	v_lshl_add_u64 v[70:71], v[4:5], 0, v[36:37]
	v_lshl_add_u64 v[72:73], v[4:5], 0, v[38:39]
	v_lshl_add_u64 v[74:75], v[4:5], 0, v[40:41]
	global_load_dwordx2 v[46:47], v[46:47], off
	global_load_dwordx2 v[48:49], v[48:49], off
	global_load_dwordx2 v[50:51], v[50:51], off
	global_load_dwordx2 v[52:53], v[52:53], off
	global_load_dwordx2 v[54:55], v[54:55], off
	global_load_dwordx2 v[56:57], v[56:57], off
	global_load_dwordx2 v[58:59], v[58:59], off
	global_load_dwordx2 v[60:61], v[60:61], off
	global_load_dwordx2 v[66:67], v[66:67], off
	global_load_dwordx2 v[68:69], v[68:69], off
	global_load_dwordx2 v[62:63], v[62:63], off
	global_load_dwordx2 v[64:65], v[64:65], off
	global_load_dwordx2 v[70:71], v[70:71], off
	global_load_dwordx2 v[72:73], v[72:73], off
	global_load_dwordx2 v[74:75], v[74:75], off
	global_load_dwordx2 v[44:45], v[44:45], off
	v_lshl_add_u64 v[12:13], v[6:7], 0, v[12:13]
	global_store_dwordx2 v[12:13], v[0:1], off
	v_lshl_add_u64 v[14:15], v[6:7], 0, v[14:15]
	v_lshl_add_u64 v[16:17], v[6:7], 0, v[16:17]
	v_lshl_add_u64 v[18:19], v[6:7], 0, v[18:19]
	v_lshl_add_u64 v[20:21], v[6:7], 0, v[20:21]
	v_lshl_add_u64 v[22:23], v[6:7], 0, v[22:23]
	v_lshl_add_u64 v[24:25], v[6:7], 0, v[24:25]
	v_lshl_add_u64 v[26:27], v[6:7], 0, v[26:27]
	v_lshl_add_u64 v[28:29], v[6:7], 0, v[28:29]
	v_lshl_add_u64 v[30:31], v[6:7], 0, v[30:31]
	v_lshl_add_u64 v[32:33], v[6:7], 0, v[32:33]
	v_lshl_add_u64 v[34:35], v[6:7], 0, v[34:35]
	v_lshl_add_u64 v[36:37], v[6:7], 0, v[36:37]
	v_lshl_add_u64 v[38:39], v[6:7], 0, v[38:39]
	v_lshl_add_u64 v[40:41], v[6:7], 0, v[40:41]
	s_add_i32 s6, s6, 16
	v_lshl_add_u64 v[42:43], v[6:7], 0, v[42:43]
	v_add_u32_e32 v8, 64, v8
	s_cmp_gt_u32 s6, 47
	s_waitcnt vmcnt(16)
	v_pk_fma_f32 v[0:1], v[2:3], v[0:1], v[46:47]
	s_waitcnt vmcnt(15)
	v_pk_fma_f32 v[12:13], v[2:3], v[0:1], v[48:49]
	global_store_dwordx2 v[14:15], v[0:1], off
	s_waitcnt vmcnt(15)
	v_pk_fma_f32 v[0:1], v[2:3], v[12:13], v[50:51]
	global_store_dwordx2 v[16:17], v[12:13], off
	s_waitcnt vmcnt(15)
	v_pk_fma_f32 v[12:13], v[2:3], v[0:1], v[52:53]
	global_store_dwordx2 v[18:19], v[0:1], off
	s_waitcnt vmcnt(15)
	v_pk_fma_f32 v[0:1], v[2:3], v[12:13], v[54:55]
	global_store_dwordx2 v[20:21], v[12:13], off
	s_waitcnt vmcnt(15)
	v_pk_fma_f32 v[12:13], v[2:3], v[0:1], v[56:57]
	global_store_dwordx2 v[22:23], v[0:1], off
	s_waitcnt vmcnt(15)
	v_pk_fma_f32 v[0:1], v[2:3], v[12:13], v[58:59]
	global_store_dwordx2 v[24:25], v[12:13], off
	s_waitcnt vmcnt(15)
	v_pk_fma_f32 v[12:13], v[2:3], v[0:1], v[60:61]
	global_store_dwordx2 v[26:27], v[0:1], off
	s_waitcnt vmcnt(13)
	v_pk_fma_f32 v[0:1], v[2:3], v[12:13], v[62:63]
	global_store_dwordx2 v[28:29], v[12:13], off
	global_store_dwordx2 v[30:31], v[0:1], off
	s_waitcnt vmcnt(14)
	v_pk_fma_f32 v[0:1], v[2:3], v[0:1], v[64:65]
	global_store_dwordx2 v[32:33], v[0:1], off
	v_pk_fma_f32 v[0:1], v[2:3], v[0:1], v[66:67]
	global_store_dwordx2 v[34:35], v[0:1], off
	v_pk_fma_f32 v[0:1], v[2:3], v[0:1], v[68:69]
	global_store_dwordx2 v[36:37], v[0:1], off
	s_waitcnt vmcnt(16)
	v_pk_fma_f32 v[0:1], v[2:3], v[0:1], v[70:71]
	global_store_dwordx2 v[38:39], v[0:1], off
	s_waitcnt vmcnt(16)
	v_pk_fma_f32 v[0:1], v[2:3], v[0:1], v[72:73]
	global_store_dwordx2 v[40:41], v[0:1], off
	s_waitcnt vmcnt(16)
	v_pk_fma_f32 v[0:1], v[2:3], v[0:1], v[74:75]
	global_store_dwordx2 v[42:43], v[0:1], off
	s_waitcnt vmcnt(16)
	v_pk_fma_f32 v[0:1], v[2:3], v[0:1], v[44:45]
	s_cbranch_scc0 .LBB0_413
	v_add_u32_e32 v10, s64, v10
	s_mov_b32 s6, 0x1ffff
	v_cmp_lt_i32_e32 vcc, s6, v10
	s_or_b64 s[4:5], vcc, s[4:5]
	s_andn2_b64 exec, exec, s[4:5]
	s_cbranch_execnz .LBB0_412

; DEV void kv_store(const uint4 k0, const uint4 k1, const uint4 v0, const uint4 v1, u16* sK, u16* sVt, int tid) {
;   const int c0 = tid, c1 = tid + NT;
;   *(uint4*)(sK + (c0 >> 4) * KS + (c0 & 15) * 8) = k0;
;   *(uint4*)(sK + (c1 >> 4) * KS + (c1 & 15) * 8) = k1;
;   vt_store(v0, sVt, c0);
;   vt_store(v1, sVt, c1);
; }
; DEV void sb_item(const Params& p, int item, unsigned char* smem) {
;   const int qb = 63 - (item & 63), h = (item >> 6) & 3, b = item >> 8;
;   const int tid = tidx(), w = tid >> 6, lane = tid & 63, fr = lane & 15, fq = lane >> 4;
;   u16* sP = (u16*)(smem + L_PW) + w * RW * VS;
;   int* flags = (int*)(smem + L_FLAG);
;   const u16* base = p.proj + (size_t)b * SEQ * DIN;
;   const int q0 = qb * QR + w * RW;
;   bf16x8 qf[MT][4];
;   load_qfrags(base + (size_t)q0 * DIN + C_SQ + h * 128, qf, fr, fq);
;   f32x4 o[MT][8];
;   float run[MT][4];
; #pragma unroll
;   for (int mt = 0; mt < MT; ++mt) {
; #pragma unroll
;     for (int nt = 0; nt < 8; ++nt) o[mt][nt] = (f32x4){0.f, 0.f, 0.f, 0.f};
; #pragma unroll
;     for (int j = 0; j < 4; ++j) run[mt][j] = 0.f;
;   }
;   const float scale = 0.08838834764831845f;
;   uint4 kq0, kq1, vq0, vq1;
;   {
;     const int kt0 = (qb * QR + QR - 1) / 64;
;     kv_load(base + (size_t)(kt0 * 64) * DIN + C_SK + h * 128, base + (size_t)(kt0 * 64) * DIN + C_SV + h * 128, kq0, kq1, vq0, vq1, tid);
;   }
;   __syncthreads();
;   int it = 0;
;     ...
;     u16* sK = (u16*)(smem + L_K + (it & 1) * KB_B); u16* sVt = (u16*)(smem + L_VT + (it & 1) * VB_B);
;     kv_store(kq0, kq1, vq0, vq1, sK, sVt, tid);
;     if (kt > 0) kv_load(base + (size_t)((kt - 1) * 64) * DIN + C_SK + h * 128, base + (size_t)((kt - 1) * 64) * DIN + C_SV + h * 128, kq0, kq1, vq0, vq1, tid);
;     __syncthreads();
.LBB0_422:
	s_ashr_i32 s92, s34, 8
	v_readfirstlane_b32 s0, v160
	s_andn2_b32 s0, s0, 63
	s_mul_i32 s1, s92, 0x5000000
	v_or_b32_e32 v51, s0, v161
	s_mul_hi_i32 s0, s92, 0x5000000
	s_add_u32 s12, s76, s1
	s_addc_u32 s13, s77, s0
	s_not_b32 s0, s34
	s_lshl_b32 s0, s0, 7
	s_and_b32 s14, s0, 0x1f80
	v_ashrrev_i32_e32 v49, 6, v51
	v_lshl_add_u32 v80, v49, 4, s14
	v_mov_b64_e32 v[0:1], s[12:13]
	v_mad_i64_i32 v[0:1], s[0:1], v80, s88, v[0:1]
	s_lshl_b32 s0, s34, 1
	s_lshr_b32 s35, s14, 6
	s_and_b32 s0, s0, 0x180
	s_or_b32 s4, s35, 1
	s_lshl_b32 s18, s0, 1
	s_mul_i32 s0, s4, 0xa0000
	s_add_u32 s0, s12, s0
	s_addc_u32 s1, s13, 0
	v_and_b32_e32 v92, 15, v51
	s_add_u32 s0, s0, s18
	v_mul_u32_u24_e32 v2, 0x1400, v92
	s_addc_u32 s1, s1, 0
	v_lshlrev_b32_e32 v6, 3, v51
	v_and_b32_e32 v48, 63, v51
	v_lshl_add_u64 v[0:1], v[0:1], 0, s[18:19]
	v_lshlrev_b32_e32 v128, 1, v2
	s_add_u32 s6, s0, 0x1400
	v_and_b32_e32 v6, 0x78, v6
	v_lshl_add_u64 v[0:1], v[0:1], 0, v[128:129]
	s_addc_u32 s7, s1, 0
	v_add_u32_e32 v10, 0x200, v51
	v_lshlrev_b32_e32 v128, 1, v6
	v_mul_u32_u24_e32 v6, 0x1400, v48
	v_ashrrev_i32_e32 v8, 3, v51
	v_ashrrev_i32_e32 v64, 4, v51
	v_mov_b64_e32 v[2:3], s[6:7]
	v_lshlrev_b32_e32 v82, 1, v6
	v_mov_b32_e32 v83, v129
	v_and_b32_e32 v84, -8, v8
	v_ashrrev_i32_e32 v65, 4, v10
	v_mad_i64_i32 v[4:5], s[6:7], v64, s88, v[2:3]
	v_lshl_add_u64 v[32:33], s[0:1], 0, v[82:83]
	v_ashrrev_i32_e32 v85, 31, v84
	v_mad_i64_i32 v[2:3], s[6:7], v65, s88, v[2:3]
	v_lshl_add_u64 v[4:5], v[4:5], 0, v[128:129]
	v_lshl_add_u64 v[6:7], v[32:33], 0, s[90:91]
	v_lshlrev_b64 v[34:35], 1, v[84:85]
	v_lshl_add_u64 v[2:3], v[2:3], 0, v[128:129]
	v_lshl_add_u64 v[8:9], v[6:7], 0, v[34:35]
	global_load_dwordx4 v[16:19], v[4:5], off
	global_load_dwordx4 v[20:23], v[2:3], off
	global_load_dwordx4 v[24:27], v[8:9], off
	v_ashrrev_i32_e32 v2, 3, v10
	v_and_b32_e32 v86, -8, v2
	v_ashrrev_i32_e32 v87, 31, v86
	v_lshlrev_b64 v[36:37], 1, v[86:87]
	v_lshl_add_u64 v[2:3], v[6:7], 0, v[36:37]
	global_load_dwordx4 v[28:31], v[2:3], off
	v_and_b32_e32 v38, 48, v51
	v_mov_b32_e32 v39, v129
	v_lshl_add_u64 v[4:5], v[0:1], 0, v[38:39]
	v_add_co_u32_e32 v0, vcc, s61, v4
	s_mov_b64 s[6:7], 0x1000
	s_nop 0
	v_addc_co_u32_e32 v1, vcc, 0, v5, vcc
	global_load_dwordx4 v[0:3], v[0:1], off
	v_lshl_add_u64 v[12:13], v[4:5], 0, s[6:7]
	global_load_dwordx4 v[4:7], v[12:13], off offset:64
	global_load_dwordx4 v[8:11], v[12:13], off offset:128
	global_load_dwordx4 v[12:15], v[12:13], off offset:192
	v_mul_lo_u32 v93, v64, s89
	s_add_u32 s0, s0, 0xfff61400
	v_lshlrev_b32_e32 v95, 1, v48
	v_mul_lo_u32 v96, v65, s89
	v_mul_lo_u32 v97, v84, s30
	v_mul_lo_u32 v98, v86, s30
	v_add_u32_e32 v40, v93, v128
	s_addc_u32 s1, s1, -1
	v_or_b32_e32 v39, v97, v95
	v_add_u32_e32 v41, v96, v128
	s_barrier
	v_mul_u32_u24_e32 v94, 0x88, v92
	v_lshl_add_u32 v50, v94, 1, v38
	v_bfe_u32 v99, v51, 4, 2
	v_lshl_or_b32 v100, v99, 2, v80
	v_mov_b32_e32 v75, 0
	s_waitcnt vmcnt(7)
	ds_write_b128 v40, v[16:19]
	s_waitcnt vmcnt(6)
	ds_write_b128 v41, v[20:23]
	s_waitcnt vmcnt(5)
	ds_write_b16 v39, v24 offset:34816
	ds_write_b16_d16_hi v39, v24 offset:34960
	ds_write_b16 v39, v25 offset:35104
	ds_write_b16_d16_hi v39, v25 offset:35248
	ds_write_b16 v39, v26 offset:35392
	ds_write_b16_d16_hi v39, v26 offset:35536
	ds_write_b16 v39, v27 offset:35680
	ds_write_b16_d16_hi v39, v27 offset:35824
	v_or_b32_e32 v16, v98, v95
	v_mov_b64_e32 v[24:25], s[0:1]
	s_waitcnt vmcnt(4)
	ds_write_b16 v16, v28 offset:34816
	ds_write_b16_d16_hi v16, v28 offset:34960
	ds_write_b16 v16, v29 offset:35104
	ds_write_b16_d16_hi v16, v29 offset:35248
	ds_write_b16 v16, v30 offset:35392
	ds_write_b16_d16_hi v16, v30 offset:35536
	ds_write_b16 v16, v31 offset:35680
	ds_write_b16_d16_hi v16, v31 offset:35824
	v_mad_i64_i32 v[16:17], s[0:1], v64, s88, v[24:25]
	s_mov_b32 s0, 0xfff61800
	s_mov_b32 s1, -1
	v_lshl_add_u64 v[28:29], v[32:33], 0, s[0:1]
	v_mad_i64_i32 v[24:25], s[0:1], v65, s88, v[24:25]
	v_lshl_add_u64 v[16:17], v[16:17], 0, v[128:129]
	v_lshl_add_u64 v[20:21], v[28:29], 0, v[34:35]
	v_lshl_add_u64 v[24:25], v[24:25], 0, v[128:129]
	v_lshl_add_u64 v[28:29], v[28:29], 0, v[36:37]
	global_load_dwordx4 v[16:19], v[16:17], off
	global_load_dwordx4 v[20:23], v[20:21], off
	global_load_dwordx4 v[24:27], v[24:25], off
	global_load_dwordx4 v[28:31], v[28:29], off
	s_waitcnt lgkmcnt(0)
	s_barrier
; DEV void sb_item(const Params& p, int item, unsigned char* smem) {
;     ...
;     qk_tile(qf, sK, s, fr, fq);
; #pragma unroll
;     for (int mt = 0; mt < MT; ++mt)
; #pragma unroll
;       for (int j = 0; j < 4; ++j) {
;         const int tq = q0 + mt * 16 + fq * 4 + j;
;         float lk[4], lb[4], inc[4], tot[4];
; #pragma unroll
;         for (int jt = 0; jt < 4; ++jt) {
;           const int sk = kt * 64 + jt * 16 + fr;
;           const float z = s[mt][jt][j] * scale;
;           const float sp = fmaxf(z, 0.f) + __logf(1.0f + __expf(-fabsf(z)));
	ds_read_b128 v[32:35], v50
	ds_read_b128 v[52:55], v50 offset:64
	s_waitcnt vmcnt(7) lgkmcnt(1)
	v_mfma_f32_16x16x32_bf16 v[32:35], v[0:3], v[32:35], 0
	ds_read_b128 v[36:39], v50 offset:4352
	ds_read_b128 v[40:43], v50 offset:8704
	ds_read_b128 v[44:47], v50 offset:13056
	s_waitcnt vmcnt(6) lgkmcnt(3)
	v_mfma_f32_16x16x32_bf16 v[32:35], v[4:7], v[52:55], v[32:35]
	ds_read_b128 v[52:55], v50 offset:4416
	ds_read_b128 v[66:69], v50 offset:8896
	s_waitcnt lgkmcnt(4)
	v_mfma_f32_16x16x32_bf16 v[36:39], v[0:3], v[36:39], 0
	s_waitcnt lgkmcnt(1)
	v_mfma_f32_16x16x32_bf16 v[36:39], v[4:7], v[52:55], v[36:39]
	ds_read_b128 v[52:55], v50 offset:8768
	v_mfma_f32_16x16x32_bf16 v[40:43], v[0:3], v[40:43], 0
	s_waitcnt lgkmcnt(0)
	v_mfma_f32_16x16x32_bf16 v[40:43], v[4:7], v[52:55], v[40:43]
	ds_read_b128 v[52:55], v50 offset:13120
	v_mfma_f32_16x16x32_bf16 v[44:47], v[0:3], v[44:47], 0
	s_waitcnt lgkmcnt(0)
	v_mfma_f32_16x16x32_bf16 v[44:47], v[4:7], v[52:55], v[44:47]
	ds_read_b128 v[52:55], v50 offset:128
	s_waitcnt vmcnt(5) lgkmcnt(0)
	v_mfma_f32_16x16x32_bf16 v[32:35], v[8:11], v[52:55], v[32:35]
	ds_read_b128 v[52:55], v50 offset:4480
	s_waitcnt lgkmcnt(0)
	v_mfma_f32_16x16x32_bf16 v[36:39], v[8:11], v[52:55], v[36:39]
	ds_read_b128 v[52:55], v50 offset:8832
	s_waitcnt lgkmcnt(0)
	v_mfma_f32_16x16x32_bf16 v[56:59], v[8:11], v[52:55], v[40:43]
	s_nop 2
	ds_read_b128 v[40:43], v50 offset:13184
	s_waitcnt lgkmcnt(0)
	v_mfma_f32_16x16x32_bf16 v[60:63], v[8:11], v[40:43], v[44:47]
	ds_read_b128 v[40:43], v50 offset:192
	s_waitcnt vmcnt(4) lgkmcnt(0)
	v_mfma_f32_16x16x32_bf16 v[44:47], v[12:15], v[40:43], v[32:35]
	s_nop 2
	ds_read_b128 v[32:35], v50 offset:4544
	s_waitcnt lgkmcnt(0)
	v_mfma_f32_16x16x32_bf16 v[40:43], v[12:15], v[32:35], v[36:39]
	s_nop 1
	v_mul_f32_e32 v54, 0x3db504f3, v44
	v_mul_f32_e64 v32, |v54|, s31
	v_exp_f32_e32 v44, v32
	v_max_f32_e32 v52, 0, v54
	v_mfma_f32_16x16x32_bf16 v[36:39], v[12:15], v[66:69], v[56:59]
	ds_read_b128 v[32:35], v50 offset:13248
	v_add_f32_e32 v44, 1.0, v44
	v_cmp_gt_f32_e32 vcc, s84, v44
	v_mul_f32_e32 v59, 0x3db504f3, v40
	v_mul_f32_e64 v40, |v59|, s31
	v_cndmask_b32_e64 v51, 0, 32, vcc
	v_ldexp_f32 v44, v44, v51
	v_log_f32_e32 v44, v44
	v_lshl_or_b32 v51, s4, 6, v92
	s_waitcnt lgkmcnt(0)
; DEV float grp16_sum_fast(float v) {
;   v += dpp_f<0x128>(v); v += dpp_f<0x124>(v); v += dpp_f<0x122>(v); v += dpp_f<0x121>(v);
;   return v;
; }
; DEV void sb_item(const Params& p, int item, unsigned char* smem) {
;     ...
;         float lk[4], lb[4], inc[4], tot[4];
; #pragma unroll
;         for (int jt = 0; jt < 4; ++jt) {
;           const int sk = kt * 64 + jt * 16 + fr;
;           const float z = s[mt][jt][j] * scale;
;           const float sp = fmaxf(z, 0.f) + __logf(1.0f + __expf(-fabsf(z)));
;           lk[jt] = (sk < tq) ? -sp : 0.f;
;           lb[jt] = z - sp;
;           float x = lk[jt];
;           x += dpp_f<0x101>(x); x += dpp_f<0x102>(x); x += dpp_f<0x104>(x); x += dpp_f<0x108>(x);
;           inc[jt] = x;
;           tot[jt] = grp16_sum_fast(lk[jt]);
;         }
;         float after = 0.f;
; #pragma unroll
;     ...
;           const int sk = kt * 64 + jt * 16 + fr;
;           const float e = lb[jt] + (inc[jt] - lk[jt]) + after + run[mt][j];
;           const float a = (sk < tq) ? __expf(e) : 0.f;
;           sP[(mt * 16 + fq * 4 + j) * VS + jt * 16 + fr] = f2bf(a);
;           after += tot[jt];
	v_mfma_f32_16x16x32_bf16 v[32:35], v[12:15], v[32:35], v[60:63]
	v_max_f32_e32 v55, 0, v59
	v_mul_f32_e32 v53, 0x3f317217, v44
	v_fma_f32 v53, v44, s29, -v53
	v_fmac_f32_e32 v53, 0x3377d1cf, v44
	v_fmac_f32_e32 v53, 0x3f317217, v44
	v_cmp_lt_f32_e64 s[0:1], |v44|, s36
	v_mul_f32_e32 v63, 0x3db504f3, v36
	v_mul_f32_e64 v36, |v63|, s31
	v_cndmask_b32_e64 v44, v44, v53, s[0:1]
	v_cndmask_b32_e32 v53, 0, v171, vcc
	v_sub_f32_e32 v44, v44, v53
	v_add_f32_e32 v56, v52, v44
	v_cmp_lt_i32_e32 vcc, v51, v100
	v_exp_f32_e32 v36, v36
	s_nop 0
	v_cndmask_b32_e64 v44, 0, -v56, vcc
	v_add_f32_e32 v36, 1.0, v36
	s_nop 0
	v_add_f32_dpp v52, v44, v44 row_shl:1 row_mask:0xf bank_mask:0xf bound_ctrl:1
	s_nop 1
	v_add_f32_dpp v52, v52, v52 row_shl:2 row_mask:0xf bank_mask:0xf bound_ctrl:1
	s_nop 1
	v_add_f32_dpp v57, v52, v52 row_shl:4 row_mask:0xf bank_mask:0xf bound_ctrl:1
	v_exp_f32_e32 v52, v40
	v_add_f32_dpp v40, v44, v44 row_ror:8 row_mask:0xf bank_mask:0xf bound_ctrl:1
	v_mov_b32_dpp v58, v57 row_shl:8 row_mask:0xf bank_mask:0xf bound_ctrl:1
	v_add_f32_e32 v44, 1.0, v52
	v_cmp_gt_f32_e64 s[0:1], s84, v44
	v_add_f32_dpp v40, v40, v40 row_ror:4 row_mask:0xf bank_mask:0xf bound_ctrl:1
	s_nop 0
	v_cndmask_b32_e64 v52, 0, 32, s[0:1]
	v_ldexp_f32 v44, v44, v52
	v_log_f32_e32 v53, v44
	v_or_b32_e32 v52, 16, v51
	v_add_f32_dpp v40, v40, v40 row_ror:2 row_mask:0xf bank_mask:0xf bound_ctrl:1
	v_mul_f32_e32 v60, 0x3f317217, v53
	v_fma_f32 v60, v53, s29, -v60
	v_fmac_f32_e32 v60, 0x3377d1cf, v53
	v_fmac_f32_e32 v60, 0x3f317217, v53
	v_cmp_lt_f32_e64 s[4:5], |v53|, s36
	v_mov_b32_dpp v44, v40 row_ror:1 row_mask:0xf bank_mask:0xf bound_ctrl:1
	s_nop 0
	v_cndmask_b32_e64 v53, v53, v60, s[4:5]
	v_cndmask_b32_e64 v60, 0, v171, s[0:1]
	v_sub_f32_e32 v53, v53, v60
	v_add_f32_e32 v60, v55, v53
	v_cmp_lt_i32_e64 s[0:1], v52, v100
	v_cmp_gt_f32_e64 s[4:5], s84, v36
	s_nop 0
	v_cndmask_b32_e64 v53, 0, -v60, s[0:1]
	s_nop 1
	v_add_f32_dpp v55, v53, v53 row_shl:1 row_mask:0xf bank_mask:0xf bound_ctrl:1
	v_add_f32_dpp v53, v53, v53 row_ror:8 row_mask:0xf bank_mask:0xf bound_ctrl:1
	s_nop 0
	v_add_f32_dpp v55, v55, v55 row_shl:2 row_mask:0xf bank_mask:0xf bound_ctrl:1
	v_add_f32_dpp v53, v53, v53 row_ror:4 row_mask:0xf bank_mask:0xf bound_ctrl:1
	s_nop 0
	v_add_f32_dpp v61, v55, v55 row_shl:4 row_mask:0xf bank_mask:0xf bound_ctrl:1
	v_add_f32_dpp v66, v53, v53 row_ror:2 row_mask:0xf bank_mask:0xf bound_ctrl:1
	v_cndmask_b32_e64 v53, 0, 32, s[4:5]
	v_ldexp_f32 v36, v36, v53
	v_log_f32_e32 v53, v36
	v_or_b32_e32 v36, 32, v51
	v_max_f32_e32 v55, 0, v63
	v_mov_b32_dpp v62, v61 row_shl:8 row_mask:0xf bank_mask:0xf bound_ctrl:1
	v_mul_f32_e32 v68, 0x3f317217, v53
	v_fma_f32 v68, v53, s29, -v68
	v_fmac_f32_e32 v68, 0x3377d1cf, v53
	v_fmac_f32_e32 v68, 0x3f317217, v53
	v_cmp_lt_f32_e64 s[6:7], |v53|, s36
	v_mov_b32_dpp v67, v66 row_ror:1 row_mask:0xf bank_mask:0xf bound_ctrl:1
	s_nop 0
	v_cndmask_b32_e64 v53, v53, v68, s[6:7]
	v_cndmask_b32_e64 v68, 0, v171, s[4:5]
	v_sub_f32_e32 v53, v53, v68
	v_add_f32_e32 v68, v55, v53
	v_cmp_lt_i32_e64 s[4:5], v36, v100
	s_nop 1
	v_cndmask_b32_e64 v55, 0, -v68, s[4:5]
	s_nop 1
	v_add_f32_dpp v53, v55, v55 row_shl:1 row_mask:0xf bank_mask:0xf bound_ctrl:1
	v_add_f32_dpp v55, v55, v55 row_ror:8 row_mask:0xf bank_mask:0xf bound_ctrl:1
	s_nop 0
	v_add_f32_dpp v53, v53, v53 row_shl:2 row_mask:0xf bank_mask:0xf bound_ctrl:1
	v_add_f32_dpp v55, v55, v55 row_ror:4 row_mask:0xf bank_mask:0xf bound_ctrl:1
	s_nop 0
	v_add_f32_dpp v69, v53, v53 row_shl:4 row_mask:0xf bank_mask:0xf bound_ctrl:1
	v_mul_f32_e32 v53, 0x3db504f3, v32
	v_mul_f32_e64 v32, |v53|, s31
	v_exp_f32_e32 v32, v32
	v_add_f32_dpp v71, v55, v55 row_ror:2 row_mask:0xf bank_mask:0xf bound_ctrl:1
	v_max_f32_e32 v73, 0, v53
	v_mov_b32_dpp v70, v69 row_shl:8 row_mask:0xf bank_mask:0xf bound_ctrl:1
	v_add_f32_e32 v32, 1.0, v32
	v_cmp_gt_f32_e64 s[6:7], s84, v32
	v_mov_b32_dpp v72, v71 row_ror:1 row_mask:0xf bank_mask:0xf bound_ctrl:1
	s_nop 0
	v_cndmask_b32_e64 v55, 0, 32, s[6:7]
	v_ldexp_f32 v32, v32, v55
	v_log_f32_e32 v55, v32
	v_or_b32_e32 v32, 48, v51
	v_mul_f32_e32 v74, 0x3f317217, v55
	v_fma_f32 v74, v55, s29, -v74
	v_fmac_f32_e32 v74, 0x3377d1cf, v55
	v_fmac_f32_e32 v74, 0x3f317217, v55
	v_cmp_lt_f32_e64 s[10:11], |v55|, s36
	s_nop 1
	v_cndmask_b32_e64 v55, v55, v74, s[10:11]
	v_cndmask_b32_e64 v74, 0, v171, s[6:7]
	v_sub_f32_e32 v55, v55, v74
	v_add_f32_e32 v76, v73, v55
	v_cmp_lt_i32_e64 s[6:7], v32, v100
	s_nop 1
	v_cndmask_b32_e64 v55, 0, -v76, s[6:7]
	s_nop 1
	v_add_f32_dpp v73, v55, v55 row_shl:1 row_mask:0xf bank_mask:0xf bound_ctrl:1
	v_add_f32_dpp v55, v55, v55 row_ror:8 row_mask:0xf bank_mask:0xf bound_ctrl:1
	s_nop 0
	v_add_f32_dpp v73, v73, v73 row_shl:2 row_mask:0xf bank_mask:0xf bound_ctrl:1
	v_add_f32_dpp v55, v55, v55 row_ror:4 row_mask:0xf bank_mask:0xf bound_ctrl:1
	s_nop 0
	v_add_f32_dpp v77, v73, v73 row_shl:4 row_mask:0xf bank_mask:0xf bound_ctrl:1
	v_add_f32_dpp v73, v55, v55 row_ror:2 row_mask:0xf bank_mask:0xf bound_ctrl:1
	v_mov_b32_e32 v55, 0
	v_mov_b32_dpp v78, v77 row_shl:8 row_mask:0xf bank_mask:0xf bound_ctrl:1
	v_mov_b32_dpp v74, v73 row_ror:1 row_mask:0xf bank_mask:0xf bound_ctrl:1
	s_and_saveexec_b64 s[10:11], s[6:7]
	s_cbranch_execz .LBB0_424
	v_add_f32_e32 v75, v77, v78
	v_sub_f32_e32 v53, v53, v76
	v_add_f32_e32 v75, v76, v75
	v_add_f32_e32 v53, v53, v75
	v_add_f32_e32 v53, 0, v53
	v_mul_f32_e32 v53, 0x3fb8aa3b, v53
	v_exp_f32_e32 v53, v53
	s_nop 0
	v_cvt_pk_bf16_f32 v75, v53, s0

; DEV void kv_store(const uint4 k0, const uint4 k1, const uint4 v0, const uint4 v1, u16* sK, u16* sVt, int tid) {
;   const int c0 = tid, c1 = tid + NT;
;   *(uint4*)(sK + (c0 >> 4) * KS + (c0 & 15) * 8) = k0;
;   *(uint4*)(sK + (c1 >> 4) * KS + (c1 & 15) * 8) = k1;
;   vt_store(v0, sVt, c0);
;   vt_store(v1, sVt, c1);
; }
; DEV void sb_item(const Params& p, int item, unsigned char* smem) {
;     ...
;     u16* sK = (u16*)(smem + L_K + (it & 1) * KB_B); u16* sVt = (u16*)(smem + L_VT + (it & 1) * VB_B);
;     kv_store(kq0, kq1, vq0, vq1, sK, sVt, tid);
;     if (kt > 0) kv_load(base + (size_t)((kt - 1) * 64) * DIN + C_SK + h * 128, base + (size_t)((kt - 1) * 64) * DIN + C_SV + h * 128, kq0, kq1, vq0, vq1, tid);
.LBB0_434:
	s_mov_b32 s1, s46
	s_add_i32 s46, s46, 1
	s_and_b32 s47, s46, 1
	s_mul_i32 s0, s47, 0x4400
	s_lshl_b32 s6, s47, 10
	v_add3_u32 v64, s0, v93, v128
	s_add_i32 s48, s0, s6
	s_waitcnt vmcnt(3)
	ds_write_b128 v64, v[16:19]
	v_add3_u32 v64, s0, v96, v128
	s_waitcnt vmcnt(1)
	ds_write_b128 v64, v[24:27]
	v_add3_u32 v64, s48, v97, v95
	ds_write_b16 v64, v20 offset:34816
	ds_write_b16_d16_hi v64, v20 offset:34960
	ds_write_b16 v64, v21 offset:35104
	ds_write_b16_d16_hi v64, v21 offset:35248
	ds_write_b16 v64, v22 offset:35392
	ds_write_b16_d16_hi v64, v22 offset:35536
	ds_write_b16 v64, v23 offset:35680
	ds_write_b16_d16_hi v64, v23 offset:35824
	v_add3_u32 v64, s48, v98, v95
	s_cmp_eq_u32 s35, s1
	s_waitcnt vmcnt(0)
	ds_write_b16 v64, v28 offset:34816
	ds_write_b16_d16_hi v64, v28 offset:34960
	ds_write_b16 v64, v29 offset:35104
	ds_write_b16_d16_hi v64, v29 offset:35248
	ds_write_b16 v64, v30 offset:35392
	ds_write_b16_d16_hi v64, v30 offset:35536
	ds_write_b16 v64, v31 offset:35680
	ds_write_b16_d16_hi v64, v31 offset:35824
	s_cbranch_scc1 .LBB0_436
	s_mul_i32 s6, s44, 0x2800
	s_mul_hi_u32 s1, s44, 0x2800
	s_add_u32 s6, s12, s6
	s_addc_u32 s1, s13, s1
	s_add_u32 s6, s6, s18
	s_addc_u32 s7, s1, 0
	s_add_u32 s10, s6, 0x1400
	v_mov_b32_e32 v83, v129
	s_addc_u32 s11, s7, 0
	v_lshl_add_u64 v[18:19], s[6:7], 0, v[82:83]
	v_lshl_add_u64 v[16:17], s[10:11], 0, v[88:89]
	v_lshl_add_u64 v[24:25], v[18:19], 0, s[90:91]
	v_lshl_add_u64 v[26:27], s[10:11], 0, v[90:91]
	v_lshl_add_u64 v[16:17], v[16:17], 0, v[128:129]
	v_lshl_add_u64 v[20:21], v[84:85], 1, v[24:25]
	v_lshl_add_u64 v[26:27], v[26:27], 0, v[128:129]
	v_lshl_add_u64 v[28:29], v[86:87], 1, v[24:25]
	global_load_dwordx4 v[16:19], v[16:17], off
	global_load_dwordx4 v[20:23], v[20:21], off
	global_load_dwordx4 v[24:27], v[26:27], off
	global_load_dwordx4 v[28:31], v[28:29], off

; DEV void load_qfrags(const u16* __restrict__ g  , bf16x8 (&qf)[MT][4], int fr, int fq) {
; #pragma unroll
;   for (int mt = 0; mt < MT; ++mt)
; #pragma unroll
;     for (int ks = 0; ks < 4; ++ks) qf[mt][ks] = *(const bf16x8*)(g + (size_t)(mt * 16 + fr) * DIN + ks * 32 + fq * 8);
; }
; DEV void swa_item(const Params& p, int l, int item, unsigned char* smem) {
;   const int qh = item & 7, n = (item >> 3) & 63, b = item >> 9, kvh = qh >> 2;
;   const int tid = tidx(), w = tid >> 6, lane = tid & 63, fr = lane & 15, fq = lane >> 4;
;   u16* sP = (u16*)(smem + L_PW) + w * RW * VS;
;   const u16* base = p.proj + (size_t)b * SEQ * DIN;
;   const int q0 = n * QR + w * RW;
;   bf16x8 qf[MT][4];
;   load_qfrags(base + (size_t)q0 * DIN + C_AQ + qh * 128, qf, fr, fq);
;   const float sink = p.sinks[l * 8 + qh];
;   const float slope = exp2f(-(float)(qh + 1));
;   const float scale = 0.08838834764831845f;
;   f32x4 o[MT][8];
;   float m[MT][4], lsum[MT][4];
; #pragma unroll
;   for (int mt = 0; mt < MT; ++mt) {
; #pragma unroll
;     for (int nt = 0; nt < 8; ++nt) o[mt][nt] = (f32x4){0.f, 0.f, 0.f, 0.f};
; #pragma unroll
;     for (int j = 0; j < 4; ++j) { m[mt][j] = sink; lsum[mt][j] = 1.0f; }
;   }
;   constexpr int NKT = (QR + 128) / 64;
;   const int ktf = (n == 0) ? 2 : 0;
;   uint4 kq0, kq1, vq0, vq1;
;   {
;     const int k0 = n * QR - 128 + ktf * 64;
;     kv_load(base + (size_t)k0 * DIN + C_AK + kvh * 128, base + (size_t)k0 * DIN + C_AV + kvh * 128, kq0, kq1, vq0, vq1, tid);
;   }
;   __syncthreads();
.LBB0_475:
	v_readfirstlane_b32 s1, v160
	s_and_b32 s0, s7, 4
	s_ashr_i32 s2, s10, 9
	s_andn2_b32 s1, s1, 63
	s_lshl_b32 s0, s0, 6
	s_and_b32 s13, s10, 7
	s_bfe_u32 s16, s10, 0x60003
	v_or_b32_e32 v17, s1, v161
	s_ashr_i32 s3, s2, 31
	s_mul_i32 s28, s2, 0x5000000
	s_mul_hi_i32 s1, s2, 0x5000000
	v_ashrrev_i32_e32 v0, 2, v17
	s_add_u32 s14, s76, s28
	v_and_b32_e32 v48, -16, v0
	s_addc_u32 s15, s77, s1
	s_lshl_b32 s17, s16, 7
	v_and_b32_e32 v91, 15, v17
	v_add_u32_e32 v80, s17, v48
	v_mov_b64_e32 v[0:1], s[14:15]
	v_mad_i64_i32 v[0:1], s[4:5], v80, s88, v[0:1]
	s_lshl_b32 s18, s13, 8
	v_mul_u32_u24_e32 v2, 0x1400, v91
	v_bfe_u32 v102, v17, 4, 2
	v_lshl_add_u64 v[0:1], v[0:1], 0, s[18:19]
	v_lshlrev_b32_e32 v128, 1, v2
	v_lshl_add_u64 v[0:1], v[0:1], 0, v[128:129]
	v_lshlrev_b32_e32 v128, 4, v102
	v_lshl_add_u64 v[0:1], v[0:1], 0, v[128:129]
	s_mov_b64 s[4:5], 0x1c00
	v_lshl_add_u64 v[12:13], v[0:1], 0, s[4:5]
	s_or_b32 s4, s13, s6
	v_add_co_u32_e32 v8, vcc, s61, v0
	s_lshl_b32 s4, s4, 2
	v_readlane_b32 s44, v253, 6
	s_lshl_b32 s11, s13, 7
	v_addc_co_u32_e32 v9, vcc, 0, v1, vcc
	v_mov_b32_e32 v18, s4
	v_readlane_b32 s52, v253, 14
	v_readlane_b32 s53, v253, 15
	s_add_i32 s13, s13, 1
	global_load_dwordx4 v[0:3], v[12:13], off offset:64
	global_load_dwordx4 v[4:7], v[12:13], off offset:128
	global_load_dwordx4 v[8:11], v[8:9], off offset:3072
	global_load_dwordx4 v[12:15], v[12:13], off offset:192
	s_mov_b32 s4, 0x42fc0000
	global_load_dword v114, v18, s[52:53]
	v_cvt_f32_ubyte0_e32 v18, s13
	v_mul_lo_u32 v16, v48, s30
	v_cmp_lt_f32_e32 vcc, s4, v18
	v_add_u32_e32 v50, 0x11800, v16
	s_and_b64 s[4:5], vcc, exec
	v_cndmask_b32_e32 v16, 0, v167, vcc
	v_sub_f32_e32 v16, v16, v18
	v_exp_f32_e32 v18, v16
	s_cselect_b32 s4, 0xffffffc0, 0
	s_cmp_eq_u32 s16, 0
	s_cselect_b32 s13, 2, 0
	s_lshl_b32 s18, s13, 6
	s_add_i32 s41, s17, s18
	v_ldexp_f32 v85, v18, s4
	s_mul_i32 s4, s41, 0x1400
	s_add_i32 s4, s4, 0xfff60000
	s_ashr_i32 s5, s4, 31
	s_lshl_b64 s[4:5], s[4:5], 1
	s_add_u32 s14, s14, s4
	s_addc_u32 s15, s15, s5
	s_lshl_b32 s16, s10, 6
	s_and_b32 s16, s16, 0x100
	s_add_u32 s14, s14, s16
	s_waitcnt vmcnt(39)
	v_lshlrev_b32_e32 v22, 3, v17
	s_addc_u32 s15, s15, 0
	v_add_u32_e32 v32, 0x200, v17
	v_ashrrev_i32_e32 v51, 4, v17
	v_and_b32_e32 v22, 0x78, v22
	v_and_b32_e32 v103, 63, v17
	v_ashrrev_i32_e32 v17, 3, v17
	s_add_u32 s16, s14, 0x2400
	v_lshlrev_b32_e32 v86, 1, v22
	v_mul_u32_u24_e32 v22, 0x1400, v103
	v_and_b32_e32 v38, -8, v17
	v_ashrrev_i32_e32 v17, 4, v32
	v_ashrrev_i32_e32 v32, 3, v32
	s_addc_u32 s17, s15, 0
	v_lshlrev_b32_e32 v36, 1, v22
	v_mov_b32_e32 v37, v129
	v_and_b32_e32 v44, -8, v32
	s_waitcnt vmcnt(37)
	v_mov_b64_e32 v[28:29], s[16:17]
	v_lshl_add_u64 v[22:23], s[14:15], 0, v[36:37]
	s_mov_b64 s[14:15], 0x2600
	v_ashrrev_i32_e32 v39, 31, v38
	v_ashrrev_i32_e32 v45, 31, v44
	v_mad_i64_i32 v[20:21], s[16:17], v51, s88, v[28:29]
	v_mov_b32_e32 v87, v129
	v_lshl_add_u64 v[30:31], v[22:23], 0, s[14:15]
	v_lshlrev_b64 v[40:41], 1, v[38:39]
	v_mad_i64_i32 v[28:29], s[14:15], v17, s88, v[28:29]
	v_lshlrev_b64 v[46:47], 1, v[44:45]
	v_lshl_add_u64 v[20:21], v[20:21], 0, v[86:87]
	v_lshl_add_u64 v[24:25], v[30:31], 0, v[40:41]
	v_lshl_add_u64 v[28:29], v[28:29], 0, v[86:87]
	v_lshl_add_u64 v[32:33], v[30:31], 0, v[46:47]
	global_load_dwordx4 v[20:23], v[20:21], off
	global_load_dwordx4 v[24:27], v[24:25], off
	global_load_dwordx4 v[28:31], v[28:29], off
	global_load_dwordx4 v[32:35], v[32:33], off
	v_mul_lo_u32 v106, v38, s30
	v_lshlrev_b32_e32 v38, 2, v102
	v_or_b32_e32 v39, v80, v38
	v_or_b32_e32 v38, v48, v38
	v_mad_i64_i32 v[18:19], s[34:35], v51, s88, 0
	v_sub_u32_e32 v38, v38, v91
	v_subrev_u32_e32 v110, s18, v38
	v_mad_i64_i32 v[18:19], s[16:17], s2, v173, v[18:19]
	v_lshlrev_b32_e32 v38, 4, v91
	v_mad_i64_i32 v[42:43], s[14:15], v17, s88, 0
	v_or3_b32 v18, v18, s0, v38
	v_lshl_add_u64 v[94:95], s[76:77], 0, v[18:19]
	v_mad_i64_i32 v[18:19], s[16:17], s2, v173, v[42:43]
	v_or3_b32 v18, v18, s0, v38
	s_or_b32 s0, s28, s0
	v_lshl_add_u64 v[96:97], s[76:77], 0, v[18:19]
	v_lshl_add_u64 v[18:19], s[0:1], 0, v[40:41]
	v_lshl_add_u64 v[18:19], v[18:19], 0, v[36:37]
	v_mul_lo_u32 v107, v44, s30
	v_lshl_or_b32 v44, v91, 1, v50
	v_or_b32_e32 v45, v50, v128
	v_mul_u32_u24_e32 v108, 0x48, v91
	v_or_b32_e32 v50, 1, v39
	v_lshl_add_u64 v[98:99], s[76:77], 0, v[18:19]
	v_lshl_add_u64 v[18:19], s[0:1], 0, v[46:47]
	v_lshlrev_b32_e32 v49, 3, v102
	v_mov_b32_e32 v16, 0
	v_mul_lo_u32 v105, v17, s89
	v_mul_u32_u24_e32 v17, 0x88, v91
	v_lshl_add_u32 v109, v108, 1, v45
	v_sub_u32_e32 v87, v39, v91
	v_mul_u32_u24_e32 v45, 0x240, v102
	v_sub_u32_e32 v88, v50, v91
	v_or_b32_e32 v50, 2, v39
	v_or_b32_e32 v39, 3, v39
	v_lshl_add_u64 v[18:19], v[18:19], 0, v[36:37]
	v_mov_b32_e32 v82, 1.0
	v_ashrrev_i32_e32 v81, 31, v80
	s_mov_b32 s12, 0
	v_mul_lo_u32 v104, v51, s89
	v_sub_u32_e32 v89, v50, v91
	v_sub_u32_e32 v90, v39, v91
	s_or_b32 s14, s18, 0xffffff40
	s_sub_i32 s15, 0x50, s41
	v_lshl_add_u64 v[100:101], s[76:77], 0, v[18:19]
	v_lshlrev_b32_e32 v111, 1, v49
	v_lshlrev_b32_e32 v112, 1, v17
	v_add_u32_e32 v113, v44, v45
	s_waitcnt vmcnt(4)
	v_mov_b32_e32 v116, v114
	v_mov_b32_e32 v118, v114
	v_mov_b32_e32 v117, v114
	s_mov_b32 s16, 0
	v_mov_b32_e32 v17, v16
	v_mov_b32_e32 v18, v16
	v_mov_b32_e32 v19, v16
	v_mov_b32_e32 v36, v16
	v_mov_b32_e32 v37, v16
	v_mov_b32_e32 v38, v16
	v_mov_b32_e32 v39, v16
	v_mov_b32_e32 v40, v16
	v_mov_b32_e32 v41, v16
	v_mov_b32_e32 v42, v16
	v_mov_b32_e32 v43, v16
	v_mov_b32_e32 v44, v16
	v_mov_b32_e32 v45, v16
	v_mov_b32_e32 v46, v16
	v_mov_b32_e32 v47, v16
	v_mov_b32_e32 v48, v16
	v_mov_b32_e32 v49, v16
	v_mov_b32_e32 v50, v16
	v_mov_b32_e32 v51, v16
	v_mov_b32_e32 v52, v16
	v_mov_b32_e32 v53, v16
	v_mov_b32_e32 v54, v16
	v_mov_b32_e32 v55, v16
	v_mov_b32_e32 v56, v16
	v_mov_b32_e32 v57, v16
	v_mov_b32_e32 v58, v16
	v_mov_b32_e32 v59, v16
	v_mov_b32_e32 v60, v16
	v_mov_b32_e32 v61, v16
	v_mov_b32_e32 v62, v16
	v_mov_b32_e32 v63, v16
	v_mov_b32_e32 v83, v82
	v_mov_b32_e32 v92, v82
	v_mov_b32_e32 v93, v82
	v_readlane_b32 s45, v253, 7
	v_readlane_b32 s46, v253, 8
	v_readlane_b32 s47, v253, 9
	v_readlane_b32 s48, v253, 10
	v_readlane_b32 s49, v253, 11
	v_readlane_b32 s50, v253, 12
	v_readlane_b32 s51, v253, 13
	v_readlane_b32 s54, v253, 16
	v_readlane_b32 s55, v253, 17
	v_readlane_b32 s56, v253, 18
	v_readlane_b32 s57, v253, 19
	v_readlane_b32 s58, v253, 20
	v_readlane_b32 s59, v253, 21
	s_waitcnt lgkmcnt(0)
	s_barrier
	s_branch .LBB0_477

; DEV void kv_store(const uint4 k0, const uint4 k1, const uint4 v0, const uint4 v1, u16* sK, u16* sVt, int tid) {
;   const int c0 = tid, c1 = tid + NT;
;   *(uint4*)(sK + (c0 >> 4) * KS + (c0 & 15) * 8) = k0;
;   *(uint4*)(sK + (c1 >> 4) * KS + (c1 & 15) * 8) = k1;
;   vt_store(v0, sVt, c0);
;   vt_store(v1, sVt, c1);
; }
; DEV void swa_item(const Params& p, int l, int item, unsigned char* smem) {
;     ...
;   for (int kt = ktf; kt < NKT; ++kt, ++it) {
;     const int key0 = n * QR - 128 + kt * 64;
;     u16* sK = (u16*)(smem + L_K + (it & 1) * KB_B); u16* sVt = (u16*)(smem + L_VT + (it & 1) * VB_B);
;     kv_store(kq0, kq1, vq0, vq1, sK, sVt, tid);
;     if (kt + 1 < NKT) kv_load(base + (size_t)(key0 + 64) * DIN + C_AK + kvh * 128, base + (size_t)(key0 + 64) * DIN + C_AV + kvh * 128, kq0, kq1, vq0, vq1, tid);
.LBB0_477:
	s_and_b32 s1, s16, 1
	s_mul_i32 s0, s1, 0x4400
	v_add3_u32 v64, s0, v104, v86
	s_lshl_b32 s1, s1, 10
	s_waitcnt vmcnt(3)
	ds_write_b128 v64, v[20:23]
	v_add3_u32 v64, s0, v105, v86
	s_add_i32 s17, s0, s1
	s_waitcnt vmcnt(1)
	ds_write_b128 v64, v[28:31]
	v_lshlrev_b32_e32 v64, 1, v103
	v_add3_u32 v65, s17, v106, v64
	v_add3_u32 v64, s17, v107, v64
	s_cmp_eq_u32 s14, s12
	ds_write_b16 v65, v24 offset:34816
	ds_write_b16_d16_hi v65, v24 offset:34960
	ds_write_b16 v65, v25 offset:35104
	ds_write_b16_d16_hi v65, v25 offset:35248
	ds_write_b16 v65, v26 offset:35392
	ds_write_b16_d16_hi v65, v26 offset:35536
	ds_write_b16 v65, v27 offset:35680
	ds_write_b16_d16_hi v65, v27 offset:35824
	s_waitcnt vmcnt(0)
	ds_write_b16 v64, v32 offset:34816
	ds_write_b16_d16_hi v64, v32 offset:34960
	ds_write_b16 v64, v33 offset:35104
	ds_write_b16_d16_hi v64, v33 offset:35248
	ds_write_b16 v64, v34 offset:35392
	ds_write_b16_d16_hi v64, v34 offset:35536
	ds_write_b16 v64, v35 offset:35680
	ds_write_b16_d16_hi v64, v35 offset:35824
	s_cbranch_scc1 .LBB0_476
	v_lshl_add_u64 v[20:21], v[94:95], 0, s[4:5]
	v_add_co_u32_e32 v20, vcc, 0xa2000, v20
	v_lshl_add_u64 v[24:25], v[98:99], 0, s[4:5]
	s_nop 0
	v_addc_co_u32_e32 v21, vcc, 0, v21, vcc
	v_add_co_u32_e32 v24, vcc, 0xa2000, v24
	v_lshl_add_u64 v[28:29], v[96:97], 0, s[4:5]
	s_nop 0
	v_addc_co_u32_e32 v25, vcc, 0, v25, vcc
	v_add_co_u32_e32 v28, vcc, 0xa2000, v28
	v_lshl_add_u64 v[32:33], v[100:101], 0, s[4:5]
	s_nop 0
	v_addc_co_u32_e32 v29, vcc, 0, v29, vcc
	v_add_co_u32_e32 v32, vcc, 0xa2000, v32
	global_load_dwordx4 v[20:23], v[20:21], off offset:1024
	s_nop 0
	v_addc_co_u32_e32 v33, vcc, 0, v33, vcc
	global_load_dwordx4 v[24:27], v[24:25], off offset:1536
	global_load_dwordx4 v[28:31], v[28:29], off offset:1024
	global_load_dwordx4 v[32:35], v[32:33], off offset:1536
	s_branch .LBB0_476

; DEV float4 ld_nt4(const float4* p) { const f32x4 v = __builtin_nontemporal_load((const f32x4*)p); return make_float4(v[0], v[1], v[2], v[3]); }
; DEV void phase_prenorm(const float* __restrict__ x, const float* __restrict__ w, u16* __restrict__ h) {
;   const int tid = tidx(), lane = tid & 63;
;   const int wave = blockIdx.x * NW + (tid >> 6), nwaves = gridDim.x * NW;
;   float4 tx[8];
;   if (wave < TOK) {
;     const float4* xr = (const float4*)(x + (size_t)wave * DM);
; #pragma unroll
;     for (int i = 0; i < 8; ++i) tx[i] = ld_nt4(xr + i * 64 + lane);
;   }
;   for (int row = wave; row < TOK; row += nwaves) {
;     float4 v[8];
;     float ss = 0.f;
; #pragma unroll
;     for (int i = 0; i < 8; ++i) { v[i] = tx[i]; ss += v[i].x * v[i].x + v[i].y * v[i].y + v[i].z * v[i].z + v[i].w * v[i].w; }
;     if (row + nwaves < TOK) {
;       const float4* xr = (const float4*)(x + (size_t)(row + nwaves) * DM);
; #pragma unroll
;       for (int i = 0; i < 8; ++i) tx[i] = ld_nt4(xr + i * 64 + lane);
;     }
;     ss = wave_sum(ss);
;     const float rs = rsqrtf(ss * (1.0f / DM) + 1e-6f);
;     uint2* hr = (uint2*)(h + (size_t)row * DM);
.LBB0_618:
	v_readfirstlane_b32 s0, v160
	s_andn2_b32 s0, s0, 63
	s_nop 0
	v_or_b32_e32 v0, s0, v161
	v_readlane_b32 s0, v253, 42
	v_ashrrev_i32_e32 v1, 6, v0
	s_nop 0
	v_add_u32_e32 v96, s0, v1
	v_cmp_gt_i32_e32 vcc, s60, v96
	s_and_saveexec_b64 s[2:3], vcc
	s_cbranch_execz .LBB0_623
	v_ashrrev_i32_e32 v97, 31, v96
	v_readlane_b32 s44, v253, 6
	v_and_b32_e32 v66, 63, v0
	v_lshlrev_b64 v[0:1], 13, v[96:97]
	v_readlane_b32 s45, v253, 7
	v_lshlrev_b32_e32 v128, 4, v66
	v_readlane_b32 s54, v253, 16
	v_lshl_add_u64 v[0:1], s[44:45], 0, v[0:1]
	v_lshl_add_u64 v[0:1], v[0:1], 0, v[128:129]
	global_load_dwordx4 v[24:27], v[0:1], off nt
	global_load_dwordx4 v[28:31], v[0:1], off offset:1024 nt
	global_load_dwordx4 v[32:35], v[0:1], off offset:2048 nt
	global_load_dwordx4 v[36:39], v[0:1], off offset:3072 nt
	v_add_co_u32_e32 v0, vcc, s61, v0
	v_readlane_b32 s55, v253, 17
	s_nop 0
	v_addc_co_u32_e32 v1, vcc, 0, v1, vcc
	global_load_dwordx4 v[40:43], v[0:1], off nt
	global_load_dwordx4 v[44:47], v[0:1], off offset:1024 nt
	global_load_dwordx4 v[48:51], v[0:1], off offset:2048 nt
	global_load_dwordx4 v[52:55], v[0:1], off offset:3072 nt
	global_load_dwordx4 v[0:3], v128, s[54:55]
	global_load_dwordx4 v[4:7], v128, s[54:55] offset:1024
	global_load_dwordx4 v[8:11], v128, s[54:55] offset:2048
	global_load_dwordx4 v[12:15], v128, s[54:55] offset:3072
	s_waitcnt vmcnt(0)
	v_or_b32_e32 v16, 0x1000, v128
	s_waitcnt vmcnt(46)
	v_or_b32_e32 v20, 0x1400, v128
	v_or_b32_e32 v56, 0x1800, v128
	v_or_b32_e32 v60, 0x1c00, v128
	global_load_dwordx4 v[16:19], v16, s[54:55]
	global_load_dwordx4 v[20:23], v20, s[54:55]
	global_load_dwordx4 v[56:59], v56, s[54:55]
	global_load_dwordx4 v[60:63], v60, s[54:55]
	v_readlane_b32 s4, v253, 44
	v_readlane_b32 s5, v253, 45
	s_load_dword s0, s[4:5], 0x10
	s_nop 0
	s_load_dword s4, s[4:5], 0x0
	v_lshlrev_b64 v[64:65], 12, v[96:97]
	v_lshl_or_b32 v64, v66, 3, v64
	v_lshl_add_u64 v[98:99], s[72:73], 0, v[64:65]
	s_waitcnt lgkmcnt(0)
	s_lshr_b32 s0, s0, 16
	s_cmp_lg_u32 s0, 0
	s_cselect_b64 s[0:1], -1, 0
	s_cmp_lg_u64 s[0:1], 0
	s_addc_u32 s0, s4, 0
	s_lshl_b32 s4, s0, 3
	v_add_u32_e32 v64, s4, v96
	v_ashrrev_i32_e32 v65, 31, v64
	v_lshlrev_b64 v[64:65], 13, v[64:65]
	v_readlane_b32 s0, v252, 28
	s_ashr_i32 s5, s4, 31
	v_or_b32_e32 v64, v64, v128
	v_readlane_b32 s1, v252, 29
	s_lshl_b64 s[6:7], s[4:5], 12
	s_lshl_b64 s[10:11], s[4:5], 13
	v_lshl_add_u64 v[100:101], s[0:1], 0, v[64:65]
	s_mov_b64 s[12:13], 0
	v_readlane_b32 s46, v253, 8
	v_readlane_b32 s47, v253, 9
	v_readlane_b32 s48, v253, 10
	v_readlane_b32 s49, v253, 11
	v_readlane_b32 s50, v253, 12
	v_readlane_b32 s51, v253, 13
	v_readlane_b32 s52, v253, 14
	v_readlane_b32 s53, v253, 15
	v_readlane_b32 s56, v253, 18
	v_readlane_b32 s57, v253, 19
	v_readlane_b32 s58, v253, 20
	v_readlane_b32 s59, v253, 21
	s_branch .LBB0_621
